# packed-f32 VALU (same IEEE ops per element) also for the gelu of the w_in GEMM epilogue (P4) and of the S5 pass-2 output (P6)
# speedup vs baseline: 1.0055x; 1.0007x over previous
; __device__ __forceinline__ unsigned cvt_pk_bf16(float lo, float hi) { unsigned r; asm volatile("v_cvt_pk_bf16_f32 %0, %1, %2" : "=v"(r) : "v"(lo), "v"(hi)); return r; }
; __device__ __forceinline__ float bf_lo(unsigned w) { return __uint_as_float(w << 16); }
; __device__ __forceinline__ float bf_hi(unsigned w) { return __uint_as_float(w & 0xffff0000u); }
; __device__ __forceinline__ float sigmoid_f(float x) { return __builtin_amdgcn_rcpf(1.0f + __expf(-x)); }
; __device__ __forceinline__ float gelu_t(float x) { const float u = 1.5957691216057308f * (x + 0.044715f * x * x * x); return x * sigmoid_f(u); }
;     __device__ __forceinline__ void operator()(const f32x4 (&acc)[2][2][4][2], const Unit& u, int wr, int wc, int fr, int fq) const {
;     ...
;             const bool act = (MODE == 1) && (col < act_cols);
; #pragma unroll
;             for (int ai = 0; ai < 2; ++ai)
; #pragma unroll
;                 for (int m = 0; m < 4; ++m) {
;                     const size_t row = (size_t)(row0 + ai * HALF + m * 16);
;                     f32x4 v0 = acc[ai][bj][m][0], v1 = acc[ai][bj][m][1];
;                     if (MODE == 1) { if (act) {
; #pragma unroll
;                         for (int j = 0; j < 4; ++j) { v0[j] = gelu_t(v0[j]); v1[j] = gelu_t(v1[j]); } } }
;                     if (MODE == 2) {
;                         const u32x4 y = *(const u32x4*)(Y + row * ldy + col);
;                         v0 = v0 + b0; v1 = v1 + b1;
;                         v0[0] = bf_lo(y.x) * sigmoid_f(v0[0]); v0[1] = bf_hi(y.x) * sigmoid_f(v0[1]); v0[2] = bf_lo(y.y) * sigmoid_f(v0[2]); v0[3] = bf_hi(y.y) * sigmoid_f(v0[3]);
;                         v1[0] = bf_lo(y.z) * sigmoid_f(v1[0]); v1[1] = bf_hi(y.z) * sigmoid_f(v1[1]); v1[2] = bf_lo(y.w) * sigmoid_f(v1[2]); v1[3] = bf_hi(y.w) * sigmoid_f(v1[3]);
;                     }
;                     u32x4 w; w.x = cvt_pk_bf16(v0[0], v0[1]); w.y = cvt_pk_bf16(v0[2], v0[3]); w.z = cvt_pk_bf16(v1[0], v1[1]); w.w = cvt_pk_bf16(v1[2], v1[3]);
;                     *(u32x4*)(O + row * ldc + col) = w;
.LBB0_497:
	s_mov_b32 s98, 0xbfb8aa3b
	s_mov_b32 s100, 1.0
	v_mov_b32_e32 v242, 0x3d372713
	v_mov_b32_e32 v244, 0x3fcc422a
	v_lshl_or_b32 v144, s28, 8, v148
	v_cmp_gt_i32_e32 vcc, s54, v144
	s_and_saveexec_b64 s[28:29], vcc
	s_cbranch_execz .LBB0_499
	v_pk_mul_f32 v[234:235], v[126:127], v[242:243] op_sel_hi:[1,0]
	v_pk_mul_f32 v[236:237], v[124:125], v[242:243] op_sel_hi:[1,0]
	v_pk_mul_f32 v[238:239], v[122:123], v[242:243] op_sel_hi:[1,0]
	v_pk_mul_f32 v[240:241], v[120:121], v[242:243] op_sel_hi:[1,0]
	v_pk_mul_f32 v[234:235], v[126:127], v[234:235]
	v_pk_mul_f32 v[236:237], v[124:125], v[236:237]
	v_pk_mul_f32 v[238:239], v[122:123], v[238:239]
	v_pk_mul_f32 v[240:241], v[120:121], v[240:241]
	v_pk_fma_f32 v[234:235], v[126:127], v[234:235], v[126:127]
	v_pk_fma_f32 v[236:237], v[124:125], v[236:237], v[124:125]
	v_pk_fma_f32 v[238:239], v[122:123], v[238:239], v[122:123]
	v_pk_fma_f32 v[240:241], v[120:121], v[240:241], v[120:121]
	v_pk_mul_f32 v[234:235], v[234:235], v[244:245] op_sel_hi:[1,0]
	v_pk_mul_f32 v[236:237], v[236:237], v[244:245] op_sel_hi:[1,0]
	v_pk_mul_f32 v[238:239], v[238:239], v[244:245] op_sel_hi:[1,0]
	v_pk_mul_f32 v[240:241], v[240:241], v[244:245] op_sel_hi:[1,0]
	v_pk_mul_f32 v[234:235], v[234:235], s[98:99] op_sel_hi:[1,0]
	v_pk_mul_f32 v[236:237], v[236:237], s[98:99] op_sel_hi:[1,0]
	v_pk_mul_f32 v[238:239], v[238:239], s[98:99] op_sel_hi:[1,0]
	v_pk_mul_f32 v[240:241], v[240:241], s[98:99] op_sel_hi:[1,0]
	v_exp_f32_e32 v234, v234
	v_exp_f32_e32 v235, v235
	v_exp_f32_e32 v236, v236
	v_exp_f32_e32 v237, v237
	v_exp_f32_e32 v238, v238
	v_exp_f32_e32 v239, v239
	v_exp_f32_e32 v240, v240
	v_exp_f32_e32 v241, v241
	v_pk_add_f32 v[234:235], v[234:235], s[100:101] op_sel_hi:[1,0]
	v_pk_add_f32 v[236:237], v[236:237], s[100:101] op_sel_hi:[1,0]
	v_pk_add_f32 v[238:239], v[238:239], s[100:101] op_sel_hi:[1,0]
	v_pk_add_f32 v[240:241], v[240:241], s[100:101] op_sel_hi:[1,0]
	v_rcp_f32_e32 v234, v234
	v_rcp_f32_e32 v235, v235
	v_rcp_f32_e32 v236, v236
	v_rcp_f32_e32 v237, v237
	v_rcp_f32_e32 v238, v238
	v_rcp_f32_e32 v239, v239
	v_rcp_f32_e32 v240, v240
	v_rcp_f32_e32 v241, v241
	v_pk_mul_f32 v[126:127], v[126:127], v[234:235]
	v_pk_mul_f32 v[124:125], v[124:125], v[236:237]
	v_pk_mul_f32 v[122:123], v[122:123], v[238:239]
	v_pk_mul_f32 v[120:121], v[120:121], v[240:241]
.LBB0_499:
	s_or_b64 exec, exec, s[28:29]
	v_lshl_add_u32 v152, s26, 8, v146
	v_cvt_pk_bf16_f32 v124, v124, v125
	v_cvt_pk_bf16_f32 v125, v126, v127
	v_cvt_pk_bf16_f32 v126, v120, v121
	v_mov_b64_e32 v[120:121], s[12:13]
	v_ashrrev_i32_e32 v145, 31, v144
	v_mad_i64_i32 v[120:121], s[0:1], v152, s64, v[120:121]
	v_lshl_add_u64 v[120:121], v[144:145], 1, v[120:121]
	v_cvt_pk_bf16_f32 v127, v122, v123
	global_store_dwordx4 v[120:121], v[124:127], off
	s_and_saveexec_b64 s[26:27], vcc
	s_cbranch_execz .LBB0_501
	v_pk_mul_f32 v[234:235], v[116:117], v[242:243] op_sel_hi:[1,0]
	v_pk_mul_f32 v[236:237], v[118:119], v[242:243] op_sel_hi:[1,0]
	v_pk_mul_f32 v[238:239], v[114:115], v[242:243] op_sel_hi:[1,0]
	v_pk_mul_f32 v[240:241], v[112:113], v[242:243] op_sel_hi:[1,0]
	v_pk_mul_f32 v[234:235], v[116:117], v[234:235]
	v_pk_mul_f32 v[236:237], v[118:119], v[236:237]
	v_pk_mul_f32 v[238:239], v[114:115], v[238:239]
	v_pk_mul_f32 v[240:241], v[112:113], v[240:241]
	v_pk_fma_f32 v[234:235], v[116:117], v[234:235], v[116:117]
	v_pk_fma_f32 v[236:237], v[118:119], v[236:237], v[118:119]
	v_pk_fma_f32 v[238:239], v[114:115], v[238:239], v[114:115]
	v_pk_fma_f32 v[240:241], v[112:113], v[240:241], v[112:113]
	v_pk_mul_f32 v[234:235], v[234:235], v[244:245] op_sel_hi:[1,0]
	v_pk_mul_f32 v[236:237], v[236:237], v[244:245] op_sel_hi:[1,0]
	v_pk_mul_f32 v[238:239], v[238:239], v[244:245] op_sel_hi:[1,0]
	v_pk_mul_f32 v[240:241], v[240:241], v[244:245] op_sel_hi:[1,0]
	v_pk_mul_f32 v[234:235], v[234:235], s[98:99] op_sel_hi:[1,0]
	v_pk_mul_f32 v[236:237], v[236:237], s[98:99] op_sel_hi:[1,0]
	v_pk_mul_f32 v[238:239], v[238:239], s[98:99] op_sel_hi:[1,0]
	v_pk_mul_f32 v[240:241], v[240:241], s[98:99] op_sel_hi:[1,0]
	v_exp_f32_e32 v234, v234
	v_exp_f32_e32 v235, v235
	v_exp_f32_e32 v236, v236
	v_exp_f32_e32 v237, v237
	v_exp_f32_e32 v238, v238
	v_exp_f32_e32 v239, v239
	v_exp_f32_e32 v240, v240
	v_exp_f32_e32 v241, v241
	v_pk_add_f32 v[234:235], v[234:235], s[100:101] op_sel_hi:[1,0]
	v_pk_add_f32 v[236:237], v[236:237], s[100:101] op_sel_hi:[1,0]
	v_pk_add_f32 v[238:239], v[238:239], s[100:101] op_sel_hi:[1,0]
	v_pk_add_f32 v[240:241], v[240:241], s[100:101] op_sel_hi:[1,0]
	v_rcp_f32_e32 v234, v234
	v_rcp_f32_e32 v235, v235
	v_rcp_f32_e32 v236, v236
	v_rcp_f32_e32 v237, v237
	v_rcp_f32_e32 v238, v238
	v_rcp_f32_e32 v239, v239
	v_rcp_f32_e32 v240, v240
	v_rcp_f32_e32 v241, v241
	v_pk_mul_f32 v[116:117], v[116:117], v[234:235]
	v_pk_mul_f32 v[118:119], v[118:119], v[236:237]
	v_pk_mul_f32 v[114:115], v[114:115], v[238:239]
	v_pk_mul_f32 v[112:113], v[112:113], v[240:241]
; __device__ __forceinline__ unsigned cvt_pk_bf16(float lo, float hi) { unsigned r; asm volatile("v_cvt_pk_bf16_f32 %0, %1, %2" : "=v"(r) : "v"(lo), "v"(hi)); return r; }
; __device__ __forceinline__ float bf_lo(unsigned w) { return __uint_as_float(w << 16); }
; __device__ __forceinline__ float bf_hi(unsigned w) { return __uint_as_float(w & 0xffff0000u); }
; __device__ __forceinline__ float sigmoid_f(float x) { return __builtin_amdgcn_rcpf(1.0f + __expf(-x)); }
; __device__ __forceinline__ float gelu_t(float x) { const float u = 1.5957691216057308f * (x + 0.044715f * x * x * x); return x * sigmoid_f(u); }
;     __device__ __forceinline__ void operator()(const f32x4 (&acc)[2][2][4][2], const Unit& u, int wr, int wc, int fr, int fq) const {
;     ...
;                 for (int m = 0; m < 4; ++m) {
;                     const size_t row = (size_t)(row0 + ai * HALF + m * 16);
;                     f32x4 v0 = acc[ai][bj][m][0], v1 = acc[ai][bj][m][1];
;                     if (MODE == 1) { if (act) {
; #pragma unroll
;                         for (int j = 0; j < 4; ++j) { v0[j] = gelu_t(v0[j]); v1[j] = gelu_t(v1[j]); } } }
;                     if (MODE == 2) {
;                         const u32x4 y = *(const u32x4*)(Y + row * ldy + col);
;                         v0 = v0 + b0; v1 = v1 + b1;
;                         v0[0] = bf_lo(y.x) * sigmoid_f(v0[0]); v0[1] = bf_hi(y.x) * sigmoid_f(v0[1]); v0[2] = bf_lo(y.y) * sigmoid_f(v0[2]); v0[3] = bf_hi(y.y) * sigmoid_f(v0[3]);
;                         v1[0] = bf_lo(y.z) * sigmoid_f(v1[0]); v1[1] = bf_hi(y.z) * sigmoid_f(v1[1]); v1[2] = bf_lo(y.w) * sigmoid_f(v1[2]); v1[3] = bf_hi(y.w) * sigmoid_f(v1[3]);
;                     }
;                     u32x4 w; w.x = cvt_pk_bf16(v0[0], v0[1]); w.y = cvt_pk_bf16(v0[2], v0[3]); w.z = cvt_pk_bf16(v1[0], v1[1]); w.w = cvt_pk_bf16(v1[2], v1[3]);
;                     *(u32x4*)(O + row * ldc + col) = w;
.LBB0_501:
	s_or_b64 exec, exec, s[26:27]
	v_or_b32_e32 v122, 16, v152
	v_cvt_pk_bf16_f32 v116, v116, v117
	v_cvt_pk_bf16_f32 v117, v118, v119
	v_cvt_pk_bf16_f32 v118, v112, v113
	v_mov_b64_e32 v[112:113], s[12:13]
	v_mad_i64_i32 v[112:113], s[0:1], v122, s64, v[112:113]
	v_lshl_add_u64 v[112:113], v[144:145], 1, v[112:113]
	v_cvt_pk_bf16_f32 v119, v114, v115
	global_store_dwordx4 v[112:113], v[116:119], off
	s_and_saveexec_b64 s[26:27], vcc
	s_cbranch_execz .LBB0_503
	v_pk_mul_f32 v[234:235], v[108:109], v[242:243] op_sel_hi:[1,0]
	v_pk_mul_f32 v[236:237], v[110:111], v[242:243] op_sel_hi:[1,0]
	v_pk_mul_f32 v[238:239], v[106:107], v[242:243] op_sel_hi:[1,0]
	v_pk_mul_f32 v[240:241], v[104:105], v[242:243] op_sel_hi:[1,0]
	v_pk_mul_f32 v[234:235], v[108:109], v[234:235]
	v_pk_mul_f32 v[236:237], v[110:111], v[236:237]
	v_pk_mul_f32 v[238:239], v[106:107], v[238:239]
	v_pk_mul_f32 v[240:241], v[104:105], v[240:241]
	v_pk_fma_f32 v[234:235], v[108:109], v[234:235], v[108:109]
	v_pk_fma_f32 v[236:237], v[110:111], v[236:237], v[110:111]
	v_pk_fma_f32 v[238:239], v[106:107], v[238:239], v[106:107]
	v_pk_fma_f32 v[240:241], v[104:105], v[240:241], v[104:105]
	v_pk_mul_f32 v[234:235], v[234:235], v[244:245] op_sel_hi:[1,0]
	v_pk_mul_f32 v[236:237], v[236:237], v[244:245] op_sel_hi:[1,0]
	v_pk_mul_f32 v[238:239], v[238:239], v[244:245] op_sel_hi:[1,0]
	v_pk_mul_f32 v[240:241], v[240:241], v[244:245] op_sel_hi:[1,0]
	v_pk_mul_f32 v[234:235], v[234:235], s[98:99] op_sel_hi:[1,0]
	v_pk_mul_f32 v[236:237], v[236:237], s[98:99] op_sel_hi:[1,0]
	v_pk_mul_f32 v[238:239], v[238:239], s[98:99] op_sel_hi:[1,0]
	v_pk_mul_f32 v[240:241], v[240:241], s[98:99] op_sel_hi:[1,0]
	v_exp_f32_e32 v234, v234
	v_exp_f32_e32 v235, v235
	v_exp_f32_e32 v236, v236
	v_exp_f32_e32 v237, v237
	v_exp_f32_e32 v238, v238
	v_exp_f32_e32 v239, v239
	v_exp_f32_e32 v240, v240
	v_exp_f32_e32 v241, v241
	v_pk_add_f32 v[234:235], v[234:235], s[100:101] op_sel_hi:[1,0]
	v_pk_add_f32 v[236:237], v[236:237], s[100:101] op_sel_hi:[1,0]
	v_pk_add_f32 v[238:239], v[238:239], s[100:101] op_sel_hi:[1,0]
	v_pk_add_f32 v[240:241], v[240:241], s[100:101] op_sel_hi:[1,0]
	v_rcp_f32_e32 v234, v234
	v_rcp_f32_e32 v235, v235
	v_rcp_f32_e32 v236, v236
	v_rcp_f32_e32 v237, v237
	v_rcp_f32_e32 v238, v238
	v_rcp_f32_e32 v239, v239
	v_rcp_f32_e32 v240, v240
	v_rcp_f32_e32 v241, v241
	v_pk_mul_f32 v[108:109], v[108:109], v[234:235]
	v_pk_mul_f32 v[110:111], v[110:111], v[236:237]
	v_pk_mul_f32 v[106:107], v[106:107], v[238:239]
	v_pk_mul_f32 v[104:105], v[104:105], v[240:241]
.LBB0_503:
	s_or_b64 exec, exec, s[26:27]
	v_or_b32_e32 v114, 32, v152
	v_cvt_pk_bf16_f32 v108, v108, v109
	v_cvt_pk_bf16_f32 v109, v110, v111
	v_cvt_pk_bf16_f32 v110, v104, v105
	v_mov_b64_e32 v[104:105], s[12:13]
	v_mad_i64_i32 v[104:105], s[0:1], v114, s64, v[104:105]
	v_lshl_add_u64 v[104:105], v[144:145], 1, v[104:105]
	v_cvt_pk_bf16_f32 v111, v106, v107
	global_store_dwordx4 v[104:105], v[108:111], off
	s_and_saveexec_b64 s[26:27], vcc
	s_cbranch_execz .LBB0_505
	v_pk_mul_f32 v[234:235], v[100:101], v[242:243] op_sel_hi:[1,0]
	v_pk_mul_f32 v[236:237], v[102:103], v[242:243] op_sel_hi:[1,0]
	v_pk_mul_f32 v[238:239], v[98:99], v[242:243] op_sel_hi:[1,0]
	v_pk_mul_f32 v[240:241], v[96:97], v[242:243] op_sel_hi:[1,0]
	v_pk_mul_f32 v[234:235], v[100:101], v[234:235]
	v_pk_mul_f32 v[236:237], v[102:103], v[236:237]
	v_pk_mul_f32 v[238:239], v[98:99], v[238:239]
	v_pk_mul_f32 v[240:241], v[96:97], v[240:241]
	v_pk_fma_f32 v[234:235], v[100:101], v[234:235], v[100:101]
	v_pk_fma_f32 v[236:237], v[102:103], v[236:237], v[102:103]
	v_pk_fma_f32 v[238:239], v[98:99], v[238:239], v[98:99]
	v_pk_fma_f32 v[240:241], v[96:97], v[240:241], v[96:97]
	v_pk_mul_f32 v[234:235], v[234:235], v[244:245] op_sel_hi:[1,0]
	v_pk_mul_f32 v[236:237], v[236:237], v[244:245] op_sel_hi:[1,0]
	v_pk_mul_f32 v[238:239], v[238:239], v[244:245] op_sel_hi:[1,0]
	v_pk_mul_f32 v[240:241], v[240:241], v[244:245] op_sel_hi:[1,0]
	v_pk_mul_f32 v[234:235], v[234:235], s[98:99] op_sel_hi:[1,0]
	v_pk_mul_f32 v[236:237], v[236:237], s[98:99] op_sel_hi:[1,0]
	v_pk_mul_f32 v[238:239], v[238:239], s[98:99] op_sel_hi:[1,0]
	v_pk_mul_f32 v[240:241], v[240:241], s[98:99] op_sel_hi:[1,0]
	v_exp_f32_e32 v234, v234
	v_exp_f32_e32 v235, v235
	v_exp_f32_e32 v236, v236
	v_exp_f32_e32 v237, v237
	v_exp_f32_e32 v238, v238
	v_exp_f32_e32 v239, v239
	v_exp_f32_e32 v240, v240
	v_exp_f32_e32 v241, v241
	v_pk_add_f32 v[234:235], v[234:235], s[100:101] op_sel_hi:[1,0]
	v_pk_add_f32 v[236:237], v[236:237], s[100:101] op_sel_hi:[1,0]
	v_pk_add_f32 v[238:239], v[238:239], s[100:101] op_sel_hi:[1,0]
	v_pk_add_f32 v[240:241], v[240:241], s[100:101] op_sel_hi:[1,0]
	v_rcp_f32_e32 v234, v234
	v_rcp_f32_e32 v235, v235
	v_rcp_f32_e32 v236, v236
	v_rcp_f32_e32 v237, v237
	v_rcp_f32_e32 v238, v238
	v_rcp_f32_e32 v239, v239
	v_rcp_f32_e32 v240, v240
	v_rcp_f32_e32 v241, v241
	v_pk_mul_f32 v[100:101], v[100:101], v[234:235]
	v_pk_mul_f32 v[102:103], v[102:103], v[236:237]
	v_pk_mul_f32 v[98:99], v[98:99], v[238:239]
	v_pk_mul_f32 v[96:97], v[96:97], v[240:241]
; __device__ __forceinline__ unsigned cvt_pk_bf16(float lo, float hi) { unsigned r; asm volatile("v_cvt_pk_bf16_f32 %0, %1, %2" : "=v"(r) : "v"(lo), "v"(hi)); return r; }
; __device__ __forceinline__ float bf_lo(unsigned w) { return __uint_as_float(w << 16); }
; __device__ __forceinline__ float bf_hi(unsigned w) { return __uint_as_float(w & 0xffff0000u); }
; __device__ __forceinline__ float sigmoid_f(float x) { return __builtin_amdgcn_rcpf(1.0f + __expf(-x)); }
; __device__ __forceinline__ float gelu_t(float x) { const float u = 1.5957691216057308f * (x + 0.044715f * x * x * x); return x * sigmoid_f(u); }
;     __device__ __forceinline__ void operator()(const f32x4 (&acc)[2][2][4][2], const Unit& u, int wr, int wc, int fr, int fq) const {
;     ...
;                 for (int m = 0; m < 4; ++m) {
;                     const size_t row = (size_t)(row0 + ai * HALF + m * 16);
;                     f32x4 v0 = acc[ai][bj][m][0], v1 = acc[ai][bj][m][1];
;                     if (MODE == 1) { if (act) {
; #pragma unroll
;                         for (int j = 0; j < 4; ++j) { v0[j] = gelu_t(v0[j]); v1[j] = gelu_t(v1[j]); } } }
;                     if (MODE == 2) {
;                         const u32x4 y = *(const u32x4*)(Y + row * ldy + col);
;                         v0 = v0 + b0; v1 = v1 + b1;
;                         v0[0] = bf_lo(y.x) * sigmoid_f(v0[0]); v0[1] = bf_hi(y.x) * sigmoid_f(v0[1]); v0[2] = bf_lo(y.y) * sigmoid_f(v0[2]); v0[3] = bf_hi(y.y) * sigmoid_f(v0[3]);
;                         v1[0] = bf_lo(y.z) * sigmoid_f(v1[0]); v1[1] = bf_hi(y.z) * sigmoid_f(v1[1]); v1[2] = bf_lo(y.w) * sigmoid_f(v1[2]); v1[3] = bf_hi(y.w) * sigmoid_f(v1[3]);
;                     }
;                     u32x4 w; w.x = cvt_pk_bf16(v0[0], v0[1]); w.y = cvt_pk_bf16(v0[2], v0[3]); w.z = cvt_pk_bf16(v1[0], v1[1]); w.w = cvt_pk_bf16(v1[2], v1[3]);
;                     *(u32x4*)(O + row * ldc + col) = w;
.LBB0_505:
	s_or_b64 exec, exec, s[26:27]
	v_or_b32_e32 v106, 48, v152
	v_cvt_pk_bf16_f32 v100, v100, v101
	v_cvt_pk_bf16_f32 v101, v102, v103
	v_cvt_pk_bf16_f32 v102, v96, v97
	v_mov_b64_e32 v[96:97], s[12:13]
	v_mad_i64_i32 v[96:97], s[0:1], v106, s64, v[96:97]
	v_lshl_add_u64 v[96:97], v[144:145], 1, v[96:97]
	v_cvt_pk_bf16_f32 v103, v98, v99
	global_store_dwordx4 v[96:97], v[100:103], off
	s_and_saveexec_b64 s[26:27], vcc
	s_cbranch_execz .LBB0_507
	v_pk_mul_f32 v[234:235], v[92:93], v[242:243] op_sel_hi:[1,0]
	v_pk_mul_f32 v[236:237], v[94:95], v[242:243] op_sel_hi:[1,0]
	v_pk_mul_f32 v[238:239], v[90:91], v[242:243] op_sel_hi:[1,0]
	v_pk_mul_f32 v[240:241], v[88:89], v[242:243] op_sel_hi:[1,0]
	v_pk_mul_f32 v[234:235], v[92:93], v[234:235]
	v_pk_mul_f32 v[236:237], v[94:95], v[236:237]
	v_pk_mul_f32 v[238:239], v[90:91], v[238:239]
	v_pk_mul_f32 v[240:241], v[88:89], v[240:241]
	v_pk_fma_f32 v[234:235], v[92:93], v[234:235], v[92:93]
	v_pk_fma_f32 v[236:237], v[94:95], v[236:237], v[94:95]
	v_pk_fma_f32 v[238:239], v[90:91], v[238:239], v[90:91]
	v_pk_fma_f32 v[240:241], v[88:89], v[240:241], v[88:89]
	v_pk_mul_f32 v[234:235], v[234:235], v[244:245] op_sel_hi:[1,0]
	v_pk_mul_f32 v[236:237], v[236:237], v[244:245] op_sel_hi:[1,0]
	v_pk_mul_f32 v[238:239], v[238:239], v[244:245] op_sel_hi:[1,0]
	v_pk_mul_f32 v[240:241], v[240:241], v[244:245] op_sel_hi:[1,0]
	v_pk_mul_f32 v[234:235], v[234:235], s[98:99] op_sel_hi:[1,0]
	v_pk_mul_f32 v[236:237], v[236:237], s[98:99] op_sel_hi:[1,0]
	v_pk_mul_f32 v[238:239], v[238:239], s[98:99] op_sel_hi:[1,0]
	v_pk_mul_f32 v[240:241], v[240:241], s[98:99] op_sel_hi:[1,0]
	v_exp_f32_e32 v234, v234
	v_exp_f32_e32 v235, v235
	v_exp_f32_e32 v236, v236
	v_exp_f32_e32 v237, v237
	v_exp_f32_e32 v238, v238
	v_exp_f32_e32 v239, v239
	v_exp_f32_e32 v240, v240
	v_exp_f32_e32 v241, v241
	v_pk_add_f32 v[234:235], v[234:235], s[100:101] op_sel_hi:[1,0]
	v_pk_add_f32 v[236:237], v[236:237], s[100:101] op_sel_hi:[1,0]
	v_pk_add_f32 v[238:239], v[238:239], s[100:101] op_sel_hi:[1,0]
	v_pk_add_f32 v[240:241], v[240:241], s[100:101] op_sel_hi:[1,0]
	v_rcp_f32_e32 v234, v234
	v_rcp_f32_e32 v235, v235
	v_rcp_f32_e32 v236, v236
	v_rcp_f32_e32 v237, v237
	v_rcp_f32_e32 v238, v238
	v_rcp_f32_e32 v239, v239
	v_rcp_f32_e32 v240, v240
	v_rcp_f32_e32 v241, v241
	v_pk_mul_f32 v[92:93], v[92:93], v[234:235]
	v_pk_mul_f32 v[94:95], v[94:95], v[236:237]
	v_pk_mul_f32 v[90:91], v[90:91], v[238:239]
	v_pk_mul_f32 v[88:89], v[88:89], v[240:241]
.LBB0_507:
	s_or_b64 exec, exec, s[26:27]
	v_add_u32_e32 v98, 0x80, v152
	v_cvt_pk_bf16_f32 v92, v92, v93
	v_cvt_pk_bf16_f32 v93, v94, v95
	v_cvt_pk_bf16_f32 v94, v88, v89
	v_mov_b64_e32 v[88:89], s[12:13]
	v_mad_i64_i32 v[88:89], s[0:1], v98, s64, v[88:89]
	v_lshl_add_u64 v[88:89], v[144:145], 1, v[88:89]
	v_cvt_pk_bf16_f32 v95, v90, v91
	global_store_dwordx4 v[88:89], v[92:95], off
	s_and_saveexec_b64 s[26:27], vcc
	s_cbranch_execz .LBB0_509
	v_pk_mul_f32 v[234:235], v[84:85], v[242:243] op_sel_hi:[1,0]
	v_pk_mul_f32 v[236:237], v[86:87], v[242:243] op_sel_hi:[1,0]
	v_pk_mul_f32 v[238:239], v[82:83], v[242:243] op_sel_hi:[1,0]
	v_pk_mul_f32 v[240:241], v[80:81], v[242:243] op_sel_hi:[1,0]
	v_pk_mul_f32 v[234:235], v[84:85], v[234:235]
	v_pk_mul_f32 v[236:237], v[86:87], v[236:237]
	v_pk_mul_f32 v[238:239], v[82:83], v[238:239]
	v_pk_mul_f32 v[240:241], v[80:81], v[240:241]
	v_pk_fma_f32 v[234:235], v[84:85], v[234:235], v[84:85]
	v_pk_fma_f32 v[236:237], v[86:87], v[236:237], v[86:87]
	v_pk_fma_f32 v[238:239], v[82:83], v[238:239], v[82:83]
	v_pk_fma_f32 v[240:241], v[80:81], v[240:241], v[80:81]
	v_pk_mul_f32 v[234:235], v[234:235], v[244:245] op_sel_hi:[1,0]
	v_pk_mul_f32 v[236:237], v[236:237], v[244:245] op_sel_hi:[1,0]
	v_pk_mul_f32 v[238:239], v[238:239], v[244:245] op_sel_hi:[1,0]
	v_pk_mul_f32 v[240:241], v[240:241], v[244:245] op_sel_hi:[1,0]
	v_pk_mul_f32 v[234:235], v[234:235], s[98:99] op_sel_hi:[1,0]
	v_pk_mul_f32 v[236:237], v[236:237], s[98:99] op_sel_hi:[1,0]
	v_pk_mul_f32 v[238:239], v[238:239], s[98:99] op_sel_hi:[1,0]
	v_pk_mul_f32 v[240:241], v[240:241], s[98:99] op_sel_hi:[1,0]
	v_exp_f32_e32 v234, v234
	v_exp_f32_e32 v235, v235
	v_exp_f32_e32 v236, v236
	v_exp_f32_e32 v237, v237
	v_exp_f32_e32 v238, v238
	v_exp_f32_e32 v239, v239
	v_exp_f32_e32 v240, v240
	v_exp_f32_e32 v241, v241
	v_pk_add_f32 v[234:235], v[234:235], s[100:101] op_sel_hi:[1,0]
	v_pk_add_f32 v[236:237], v[236:237], s[100:101] op_sel_hi:[1,0]
	v_pk_add_f32 v[238:239], v[238:239], s[100:101] op_sel_hi:[1,0]
	v_pk_add_f32 v[240:241], v[240:241], s[100:101] op_sel_hi:[1,0]
	v_rcp_f32_e32 v234, v234
	v_rcp_f32_e32 v235, v235
	v_rcp_f32_e32 v236, v236
	v_rcp_f32_e32 v237, v237
	v_rcp_f32_e32 v238, v238
	v_rcp_f32_e32 v239, v239
	v_rcp_f32_e32 v240, v240
	v_rcp_f32_e32 v241, v241
	v_pk_mul_f32 v[84:85], v[84:85], v[234:235]
	v_pk_mul_f32 v[86:87], v[86:87], v[236:237]
	v_pk_mul_f32 v[82:83], v[82:83], v[238:239]
	v_pk_mul_f32 v[80:81], v[80:81], v[240:241]
; __device__ __forceinline__ unsigned cvt_pk_bf16(float lo, float hi) { unsigned r; asm volatile("v_cvt_pk_bf16_f32 %0, %1, %2" : "=v"(r) : "v"(lo), "v"(hi)); return r; }
; __device__ __forceinline__ float bf_lo(unsigned w) { return __uint_as_float(w << 16); }
; __device__ __forceinline__ float bf_hi(unsigned w) { return __uint_as_float(w & 0xffff0000u); }
; __device__ __forceinline__ float sigmoid_f(float x) { return __builtin_amdgcn_rcpf(1.0f + __expf(-x)); }
; __device__ __forceinline__ float gelu_t(float x) { const float u = 1.5957691216057308f * (x + 0.044715f * x * x * x); return x * sigmoid_f(u); }
;     __device__ __forceinline__ void operator()(const f32x4 (&acc)[2][2][4][2], const Unit& u, int wr, int wc, int fr, int fq) const {
;     ...
;                 for (int m = 0; m < 4; ++m) {
;                     const size_t row = (size_t)(row0 + ai * HALF + m * 16);
;                     f32x4 v0 = acc[ai][bj][m][0], v1 = acc[ai][bj][m][1];
;                     if (MODE == 1) { if (act) {
; #pragma unroll
;                         for (int j = 0; j < 4; ++j) { v0[j] = gelu_t(v0[j]); v1[j] = gelu_t(v1[j]); } } }
;                     if (MODE == 2) {
;                         const u32x4 y = *(const u32x4*)(Y + row * ldy + col);
;                         v0 = v0 + b0; v1 = v1 + b1;
;                         v0[0] = bf_lo(y.x) * sigmoid_f(v0[0]); v0[1] = bf_hi(y.x) * sigmoid_f(v0[1]); v0[2] = bf_lo(y.y) * sigmoid_f(v0[2]); v0[3] = bf_hi(y.y) * sigmoid_f(v0[3]);
;                         v1[0] = bf_lo(y.z) * sigmoid_f(v1[0]); v1[1] = bf_hi(y.z) * sigmoid_f(v1[1]); v1[2] = bf_lo(y.w) * sigmoid_f(v1[2]); v1[3] = bf_hi(y.w) * sigmoid_f(v1[3]);
;                     }
;                     u32x4 w; w.x = cvt_pk_bf16(v0[0], v0[1]); w.y = cvt_pk_bf16(v0[2], v0[3]); w.z = cvt_pk_bf16(v1[0], v1[1]); w.w = cvt_pk_bf16(v1[2], v1[3]);
;                     *(u32x4*)(O + row * ldc + col) = w;
.LBB0_509:
	s_or_b64 exec, exec, s[26:27]
	v_add_u32_e32 v90, 0x90, v152
	v_cvt_pk_bf16_f32 v84, v84, v85
	v_cvt_pk_bf16_f32 v85, v86, v87
	v_cvt_pk_bf16_f32 v86, v80, v81
	v_mov_b64_e32 v[80:81], s[12:13]
	v_mad_i64_i32 v[80:81], s[0:1], v90, s64, v[80:81]
	v_lshl_add_u64 v[80:81], v[144:145], 1, v[80:81]
	v_cvt_pk_bf16_f32 v87, v82, v83
	global_store_dwordx4 v[80:81], v[84:87], off
	s_and_saveexec_b64 s[26:27], vcc
	s_cbranch_execz .LBB0_511
	v_pk_mul_f32 v[234:235], v[76:77], v[242:243] op_sel_hi:[1,0]
	v_pk_mul_f32 v[236:237], v[78:79], v[242:243] op_sel_hi:[1,0]
	v_pk_mul_f32 v[238:239], v[74:75], v[242:243] op_sel_hi:[1,0]
	v_pk_mul_f32 v[240:241], v[72:73], v[242:243] op_sel_hi:[1,0]
	v_pk_mul_f32 v[234:235], v[76:77], v[234:235]
	v_pk_mul_f32 v[236:237], v[78:79], v[236:237]
	v_pk_mul_f32 v[238:239], v[74:75], v[238:239]
	v_pk_mul_f32 v[240:241], v[72:73], v[240:241]
	v_pk_fma_f32 v[234:235], v[76:77], v[234:235], v[76:77]
	v_pk_fma_f32 v[236:237], v[78:79], v[236:237], v[78:79]
	v_pk_fma_f32 v[238:239], v[74:75], v[238:239], v[74:75]
	v_pk_fma_f32 v[240:241], v[72:73], v[240:241], v[72:73]
	v_pk_mul_f32 v[234:235], v[234:235], v[244:245] op_sel_hi:[1,0]
	v_pk_mul_f32 v[236:237], v[236:237], v[244:245] op_sel_hi:[1,0]
	v_pk_mul_f32 v[238:239], v[238:239], v[244:245] op_sel_hi:[1,0]
	v_pk_mul_f32 v[240:241], v[240:241], v[244:245] op_sel_hi:[1,0]
	v_pk_mul_f32 v[234:235], v[234:235], s[98:99] op_sel_hi:[1,0]
	v_pk_mul_f32 v[236:237], v[236:237], s[98:99] op_sel_hi:[1,0]
	v_pk_mul_f32 v[238:239], v[238:239], s[98:99] op_sel_hi:[1,0]
	v_pk_mul_f32 v[240:241], v[240:241], s[98:99] op_sel_hi:[1,0]
	v_exp_f32_e32 v234, v234
	v_exp_f32_e32 v235, v235
	v_exp_f32_e32 v236, v236
	v_exp_f32_e32 v237, v237
	v_exp_f32_e32 v238, v238
	v_exp_f32_e32 v239, v239
	v_exp_f32_e32 v240, v240
	v_exp_f32_e32 v241, v241
	v_pk_add_f32 v[234:235], v[234:235], s[100:101] op_sel_hi:[1,0]
	v_pk_add_f32 v[236:237], v[236:237], s[100:101] op_sel_hi:[1,0]
	v_pk_add_f32 v[238:239], v[238:239], s[100:101] op_sel_hi:[1,0]
	v_pk_add_f32 v[240:241], v[240:241], s[100:101] op_sel_hi:[1,0]
	v_rcp_f32_e32 v234, v234
	v_rcp_f32_e32 v235, v235
	v_rcp_f32_e32 v236, v236
	v_rcp_f32_e32 v237, v237
	v_rcp_f32_e32 v238, v238
	v_rcp_f32_e32 v239, v239
	v_rcp_f32_e32 v240, v240
	v_rcp_f32_e32 v241, v241
	v_pk_mul_f32 v[76:77], v[76:77], v[234:235]
	v_pk_mul_f32 v[78:79], v[78:79], v[236:237]
	v_pk_mul_f32 v[74:75], v[74:75], v[238:239]
	v_pk_mul_f32 v[72:73], v[72:73], v[240:241]
.LBB0_511:
	s_or_b64 exec, exec, s[26:27]
	v_add_u32_e32 v82, 0xa0, v152
	v_cvt_pk_bf16_f32 v76, v76, v77
	v_cvt_pk_bf16_f32 v77, v78, v79
	v_cvt_pk_bf16_f32 v78, v72, v73
	v_mov_b64_e32 v[72:73], s[12:13]
	v_mad_i64_i32 v[72:73], s[0:1], v82, s64, v[72:73]
	v_lshl_add_u64 v[72:73], v[144:145], 1, v[72:73]
	v_cvt_pk_bf16_f32 v79, v74, v75
	global_store_dwordx4 v[72:73], v[76:79], off
	s_and_saveexec_b64 s[26:27], vcc
	s_cbranch_execz .LBB0_513
	v_pk_mul_f32 v[234:235], v[68:69], v[242:243] op_sel_hi:[1,0]
	v_pk_mul_f32 v[236:237], v[70:71], v[242:243] op_sel_hi:[1,0]
	v_pk_mul_f32 v[238:239], v[66:67], v[242:243] op_sel_hi:[1,0]
	v_pk_mul_f32 v[240:241], v[64:65], v[242:243] op_sel_hi:[1,0]
	v_pk_mul_f32 v[234:235], v[68:69], v[234:235]
	v_pk_mul_f32 v[236:237], v[70:71], v[236:237]
	v_pk_mul_f32 v[238:239], v[66:67], v[238:239]
	v_pk_mul_f32 v[240:241], v[64:65], v[240:241]
	v_pk_fma_f32 v[234:235], v[68:69], v[234:235], v[68:69]
	v_pk_fma_f32 v[236:237], v[70:71], v[236:237], v[70:71]
	v_pk_fma_f32 v[238:239], v[66:67], v[238:239], v[66:67]
	v_pk_fma_f32 v[240:241], v[64:65], v[240:241], v[64:65]
	v_pk_mul_f32 v[234:235], v[234:235], v[244:245] op_sel_hi:[1,0]
	v_pk_mul_f32 v[236:237], v[236:237], v[244:245] op_sel_hi:[1,0]
	v_pk_mul_f32 v[238:239], v[238:239], v[244:245] op_sel_hi:[1,0]
	v_pk_mul_f32 v[240:241], v[240:241], v[244:245] op_sel_hi:[1,0]
	v_pk_mul_f32 v[234:235], v[234:235], s[98:99] op_sel_hi:[1,0]
	v_pk_mul_f32 v[236:237], v[236:237], s[98:99] op_sel_hi:[1,0]
	v_pk_mul_f32 v[238:239], v[238:239], s[98:99] op_sel_hi:[1,0]
	v_pk_mul_f32 v[240:241], v[240:241], s[98:99] op_sel_hi:[1,0]
	v_exp_f32_e32 v234, v234
	v_exp_f32_e32 v235, v235
	v_exp_f32_e32 v236, v236
	v_exp_f32_e32 v237, v237
	v_exp_f32_e32 v238, v238
	v_exp_f32_e32 v239, v239
	v_exp_f32_e32 v240, v240
	v_exp_f32_e32 v241, v241
	v_pk_add_f32 v[234:235], v[234:235], s[100:101] op_sel_hi:[1,0]
	v_pk_add_f32 v[236:237], v[236:237], s[100:101] op_sel_hi:[1,0]
	v_pk_add_f32 v[238:239], v[238:239], s[100:101] op_sel_hi:[1,0]
	v_pk_add_f32 v[240:241], v[240:241], s[100:101] op_sel_hi:[1,0]
	v_rcp_f32_e32 v234, v234
	v_rcp_f32_e32 v235, v235
	v_rcp_f32_e32 v236, v236
	v_rcp_f32_e32 v237, v237
	v_rcp_f32_e32 v238, v238
	v_rcp_f32_e32 v239, v239
	v_rcp_f32_e32 v240, v240
	v_rcp_f32_e32 v241, v241
	v_pk_mul_f32 v[68:69], v[68:69], v[234:235]
	v_pk_mul_f32 v[70:71], v[70:71], v[236:237]
	v_pk_mul_f32 v[66:67], v[66:67], v[238:239]
	v_pk_mul_f32 v[64:65], v[64:65], v[240:241]
; __device__ __forceinline__ unsigned cvt_pk_bf16(float lo, float hi) { unsigned r; asm volatile("v_cvt_pk_bf16_f32 %0, %1, %2" : "=v"(r) : "v"(lo), "v"(hi)); return r; }
; __device__ __forceinline__ float bf_lo(unsigned w) { return __uint_as_float(w << 16); }
; __device__ __forceinline__ float bf_hi(unsigned w) { return __uint_as_float(w & 0xffff0000u); }
; __device__ __forceinline__ float sigmoid_f(float x) { return __builtin_amdgcn_rcpf(1.0f + __expf(-x)); }
; __device__ __forceinline__ float gelu_t(float x) { const float u = 1.5957691216057308f * (x + 0.044715f * x * x * x); return x * sigmoid_f(u); }
;     __device__ __forceinline__ void operator()(const f32x4 (&acc)[2][2][4][2], const Unit& u, int wr, int wc, int fr, int fq) const {
;     ...
;         for (int bj = 0; bj < 2; ++bj) {
;             const int col = col0 + bj * HALF;
;             f32x4 b0 = (f32x4){0.f, 0.f, 0.f, 0.f}, b1 = b0;
;             if (MODE == 2) { b0 = *(const f32x4*)(bias + col); b1 = *(const f32x4*)(bias + col + 4); }
;             const bool act = (MODE == 1) && (col < act_cols);
; #pragma unroll
;             for (int ai = 0; ai < 2; ++ai)
; #pragma unroll
;                 for (int m = 0; m < 4; ++m) {
;                     const size_t row = (size_t)(row0 + ai * HALF + m * 16);
;                     f32x4 v0 = acc[ai][bj][m][0], v1 = acc[ai][bj][m][1];
;                     if (MODE == 1) { if (act) {
; #pragma unroll
;                         for (int j = 0; j < 4; ++j) { v0[j] = gelu_t(v0[j]); v1[j] = gelu_t(v1[j]); } } }
;                     if (MODE == 2) {
;                         const u32x4 y = *(const u32x4*)(Y + row * ldy + col);
;                         v0 = v0 + b0; v1 = v1 + b1;
;                         v0[0] = bf_lo(y.x) * sigmoid_f(v0[0]); v0[1] = bf_hi(y.x) * sigmoid_f(v0[1]); v0[2] = bf_lo(y.y) * sigmoid_f(v0[2]); v0[3] = bf_hi(y.y) * sigmoid_f(v0[3]);
;                         v1[0] = bf_lo(y.z) * sigmoid_f(v1[0]); v1[1] = bf_hi(y.z) * sigmoid_f(v1[1]); v1[2] = bf_lo(y.w) * sigmoid_f(v1[2]); v1[3] = bf_hi(y.w) * sigmoid_f(v1[3]);
;                     }
;                     u32x4 w; w.x = cvt_pk_bf16(v0[0], v0[1]); w.y = cvt_pk_bf16(v0[2], v0[3]); w.z = cvt_pk_bf16(v1[0], v1[1]); w.w = cvt_pk_bf16(v1[2], v1[3]);
;                     *(u32x4*)(O + row * ldc + col) = w;
.LBB0_513:
	s_or_b64 exec, exec, s[26:27]
	v_add_u32_e32 v74, 0xb0, v152
	v_cvt_pk_bf16_f32 v68, v68, v69
	v_cvt_pk_bf16_f32 v69, v70, v71
	v_cvt_pk_bf16_f32 v70, v64, v65
	v_mov_b64_e32 v[64:65], s[12:13]
	v_cvt_pk_bf16_f32 v71, v66, v67
	v_mad_i64_i32 v[64:65], s[0:1], v74, s64, v[64:65]
	v_or_b32_e32 v66, 0x80, v144
	v_lshl_add_u64 v[64:65], v[144:145], 1, v[64:65]
	v_cmp_gt_i32_e32 vcc, s54, v66
	global_store_dwordx4 v[64:65], v[68:71], off
	s_and_saveexec_b64 s[26:27], vcc
	s_cbranch_execz .LBB0_515
	v_pk_mul_f32 v[234:235], v[60:61], v[242:243] op_sel_hi:[1,0]
	v_pk_mul_f32 v[236:237], v[62:63], v[242:243] op_sel_hi:[1,0]
	v_pk_mul_f32 v[238:239], v[58:59], v[242:243] op_sel_hi:[1,0]
	v_pk_mul_f32 v[240:241], v[56:57], v[242:243] op_sel_hi:[1,0]
	v_pk_mul_f32 v[234:235], v[60:61], v[234:235]
	v_pk_mul_f32 v[236:237], v[62:63], v[236:237]
	v_pk_mul_f32 v[238:239], v[58:59], v[238:239]
	v_pk_mul_f32 v[240:241], v[56:57], v[240:241]
	v_pk_fma_f32 v[234:235], v[60:61], v[234:235], v[60:61]
	v_pk_fma_f32 v[236:237], v[62:63], v[236:237], v[62:63]
	v_pk_fma_f32 v[238:239], v[58:59], v[238:239], v[58:59]
	v_pk_fma_f32 v[240:241], v[56:57], v[240:241], v[56:57]
	v_pk_mul_f32 v[234:235], v[234:235], v[244:245] op_sel_hi:[1,0]
	v_pk_mul_f32 v[236:237], v[236:237], v[244:245] op_sel_hi:[1,0]
	v_pk_mul_f32 v[238:239], v[238:239], v[244:245] op_sel_hi:[1,0]
	v_pk_mul_f32 v[240:241], v[240:241], v[244:245] op_sel_hi:[1,0]
	v_pk_mul_f32 v[234:235], v[234:235], s[98:99] op_sel_hi:[1,0]
	v_pk_mul_f32 v[236:237], v[236:237], s[98:99] op_sel_hi:[1,0]
	v_pk_mul_f32 v[238:239], v[238:239], s[98:99] op_sel_hi:[1,0]
	v_pk_mul_f32 v[240:241], v[240:241], s[98:99] op_sel_hi:[1,0]
	v_exp_f32_e32 v234, v234
	v_exp_f32_e32 v235, v235
	v_exp_f32_e32 v236, v236
	v_exp_f32_e32 v237, v237
	v_exp_f32_e32 v238, v238
	v_exp_f32_e32 v239, v239
	v_exp_f32_e32 v240, v240
	v_exp_f32_e32 v241, v241
	v_pk_add_f32 v[234:235], v[234:235], s[100:101] op_sel_hi:[1,0]
	v_pk_add_f32 v[236:237], v[236:237], s[100:101] op_sel_hi:[1,0]
	v_pk_add_f32 v[238:239], v[238:239], s[100:101] op_sel_hi:[1,0]
	v_pk_add_f32 v[240:241], v[240:241], s[100:101] op_sel_hi:[1,0]
	v_rcp_f32_e32 v234, v234
	v_rcp_f32_e32 v235, v235
	v_rcp_f32_e32 v236, v236
	v_rcp_f32_e32 v237, v237
	v_rcp_f32_e32 v238, v238
	v_rcp_f32_e32 v239, v239
	v_rcp_f32_e32 v240, v240
	v_rcp_f32_e32 v241, v241
	v_pk_mul_f32 v[60:61], v[60:61], v[234:235]
	v_pk_mul_f32 v[62:63], v[62:63], v[236:237]
	v_pk_mul_f32 v[58:59], v[58:59], v[238:239]
	v_pk_mul_f32 v[56:57], v[56:57], v[240:241]
.LBB0_515:
	s_or_b64 exec, exec, s[26:27]
	v_cvt_pk_bf16_f32 v60, v60, v61
	v_cvt_pk_bf16_f32 v61, v62, v63
	v_cvt_pk_bf16_f32 v62, v56, v57
	v_cvt_pk_bf16_f32 v63, v58, v59
	global_store_dwordx4 v[120:121], v[60:63], off offset:256
	s_and_saveexec_b64 s[26:27], vcc
	s_cbranch_execz .LBB0_517
	v_pk_mul_f32 v[234:235], v[52:53], v[242:243] op_sel_hi:[1,0]
	v_pk_mul_f32 v[236:237], v[54:55], v[242:243] op_sel_hi:[1,0]
	v_pk_mul_f32 v[238:239], v[50:51], v[242:243] op_sel_hi:[1,0]
	v_pk_mul_f32 v[240:241], v[48:49], v[242:243] op_sel_hi:[1,0]
	v_pk_mul_f32 v[234:235], v[52:53], v[234:235]
	v_pk_mul_f32 v[236:237], v[54:55], v[236:237]
	v_pk_mul_f32 v[238:239], v[50:51], v[238:239]
	v_pk_mul_f32 v[240:241], v[48:49], v[240:241]
	v_pk_fma_f32 v[234:235], v[52:53], v[234:235], v[52:53]
	v_pk_fma_f32 v[236:237], v[54:55], v[236:237], v[54:55]
	v_pk_fma_f32 v[238:239], v[50:51], v[238:239], v[50:51]
	v_pk_fma_f32 v[240:241], v[48:49], v[240:241], v[48:49]
	v_pk_mul_f32 v[234:235], v[234:235], v[244:245] op_sel_hi:[1,0]
	v_pk_mul_f32 v[236:237], v[236:237], v[244:245] op_sel_hi:[1,0]
	v_pk_mul_f32 v[238:239], v[238:239], v[244:245] op_sel_hi:[1,0]
	v_pk_mul_f32 v[240:241], v[240:241], v[244:245] op_sel_hi:[1,0]
	v_pk_mul_f32 v[234:235], v[234:235], s[98:99] op_sel_hi:[1,0]
	v_pk_mul_f32 v[236:237], v[236:237], s[98:99] op_sel_hi:[1,0]
	v_pk_mul_f32 v[238:239], v[238:239], s[98:99] op_sel_hi:[1,0]
	v_pk_mul_f32 v[240:241], v[240:241], s[98:99] op_sel_hi:[1,0]
	v_exp_f32_e32 v234, v234
	v_exp_f32_e32 v235, v235
	v_exp_f32_e32 v236, v236
	v_exp_f32_e32 v237, v237
	v_exp_f32_e32 v238, v238
	v_exp_f32_e32 v239, v239
	v_exp_f32_e32 v240, v240
	v_exp_f32_e32 v241, v241
	v_pk_add_f32 v[234:235], v[234:235], s[100:101] op_sel_hi:[1,0]
	v_pk_add_f32 v[236:237], v[236:237], s[100:101] op_sel_hi:[1,0]
	v_pk_add_f32 v[238:239], v[238:239], s[100:101] op_sel_hi:[1,0]
	v_pk_add_f32 v[240:241], v[240:241], s[100:101] op_sel_hi:[1,0]
	v_rcp_f32_e32 v234, v234
	v_rcp_f32_e32 v235, v235
	v_rcp_f32_e32 v236, v236
	v_rcp_f32_e32 v237, v237
	v_rcp_f32_e32 v238, v238
	v_rcp_f32_e32 v239, v239
	v_rcp_f32_e32 v240, v240
	v_rcp_f32_e32 v241, v241
	v_pk_mul_f32 v[52:53], v[52:53], v[234:235]
	v_pk_mul_f32 v[54:55], v[54:55], v[236:237]
	v_pk_mul_f32 v[50:51], v[50:51], v[238:239]
	v_pk_mul_f32 v[48:49], v[48:49], v[240:241]
; __device__ __forceinline__ unsigned cvt_pk_bf16(float lo, float hi) { unsigned r; asm volatile("v_cvt_pk_bf16_f32 %0, %1, %2" : "=v"(r) : "v"(lo), "v"(hi)); return r; }
; __device__ __forceinline__ float bf_lo(unsigned w) { return __uint_as_float(w << 16); }
; __device__ __forceinline__ float bf_hi(unsigned w) { return __uint_as_float(w & 0xffff0000u); }
; __device__ __forceinline__ float sigmoid_f(float x) { return __builtin_amdgcn_rcpf(1.0f + __expf(-x)); }
; __device__ __forceinline__ float gelu_t(float x) { const float u = 1.5957691216057308f * (x + 0.044715f * x * x * x); return x * sigmoid_f(u); }
;     __device__ __forceinline__ void operator()(const f32x4 (&acc)[2][2][4][2], const Unit& u, int wr, int wc, int fr, int fq) const {
;     ...
;                 for (int m = 0; m < 4; ++m) {
;                     const size_t row = (size_t)(row0 + ai * HALF + m * 16);
;                     f32x4 v0 = acc[ai][bj][m][0], v1 = acc[ai][bj][m][1];
;                     if (MODE == 1) { if (act) {
; #pragma unroll
;                         for (int j = 0; j < 4; ++j) { v0[j] = gelu_t(v0[j]); v1[j] = gelu_t(v1[j]); } } }
;                     if (MODE == 2) {
;                         const u32x4 y = *(const u32x4*)(Y + row * ldy + col);
;                         v0 = v0 + b0; v1 = v1 + b1;
;                         v0[0] = bf_lo(y.x) * sigmoid_f(v0[0]); v0[1] = bf_hi(y.x) * sigmoid_f(v0[1]); v0[2] = bf_lo(y.y) * sigmoid_f(v0[2]); v0[3] = bf_hi(y.y) * sigmoid_f(v0[3]);
;                         v1[0] = bf_lo(y.z) * sigmoid_f(v1[0]); v1[1] = bf_hi(y.z) * sigmoid_f(v1[1]); v1[2] = bf_lo(y.w) * sigmoid_f(v1[2]); v1[3] = bf_hi(y.w) * sigmoid_f(v1[3]);
;                     }
;                     u32x4 w; w.x = cvt_pk_bf16(v0[0], v0[1]); w.y = cvt_pk_bf16(v0[2], v0[3]); w.z = cvt_pk_bf16(v1[0], v1[1]); w.w = cvt_pk_bf16(v1[2], v1[3]);
;                     *(u32x4*)(O + row * ldc + col) = w;
.LBB0_517:
	s_or_b64 exec, exec, s[26:27]
	v_cvt_pk_bf16_f32 v52, v52, v53
	v_cvt_pk_bf16_f32 v53, v54, v55
	v_cvt_pk_bf16_f32 v54, v48, v49
	v_cvt_pk_bf16_f32 v55, v50, v51
	global_store_dwordx4 v[112:113], v[52:55], off offset:256
	s_and_saveexec_b64 s[26:27], vcc
	s_cbranch_execz .LBB0_519
	v_pk_mul_f32 v[234:235], v[44:45], v[242:243] op_sel_hi:[1,0]
	v_pk_mul_f32 v[236:237], v[46:47], v[242:243] op_sel_hi:[1,0]
	v_pk_mul_f32 v[238:239], v[42:43], v[242:243] op_sel_hi:[1,0]
	v_pk_mul_f32 v[240:241], v[40:41], v[242:243] op_sel_hi:[1,0]
	v_pk_mul_f32 v[234:235], v[44:45], v[234:235]
	v_pk_mul_f32 v[236:237], v[46:47], v[236:237]
	v_pk_mul_f32 v[238:239], v[42:43], v[238:239]
	v_pk_mul_f32 v[240:241], v[40:41], v[240:241]
	v_pk_fma_f32 v[234:235], v[44:45], v[234:235], v[44:45]
	v_pk_fma_f32 v[236:237], v[46:47], v[236:237], v[46:47]
	v_pk_fma_f32 v[238:239], v[42:43], v[238:239], v[42:43]
	v_pk_fma_f32 v[240:241], v[40:41], v[240:241], v[40:41]
	v_pk_mul_f32 v[234:235], v[234:235], v[244:245] op_sel_hi:[1,0]
	v_pk_mul_f32 v[236:237], v[236:237], v[244:245] op_sel_hi:[1,0]
	v_pk_mul_f32 v[238:239], v[238:239], v[244:245] op_sel_hi:[1,0]
	v_pk_mul_f32 v[240:241], v[240:241], v[244:245] op_sel_hi:[1,0]
	v_pk_mul_f32 v[234:235], v[234:235], s[98:99] op_sel_hi:[1,0]
	v_pk_mul_f32 v[236:237], v[236:237], s[98:99] op_sel_hi:[1,0]
	v_pk_mul_f32 v[238:239], v[238:239], s[98:99] op_sel_hi:[1,0]
	v_pk_mul_f32 v[240:241], v[240:241], s[98:99] op_sel_hi:[1,0]
	v_exp_f32_e32 v234, v234
	v_exp_f32_e32 v235, v235
	v_exp_f32_e32 v236, v236
	v_exp_f32_e32 v237, v237
	v_exp_f32_e32 v238, v238
	v_exp_f32_e32 v239, v239
	v_exp_f32_e32 v240, v240
	v_exp_f32_e32 v241, v241
	v_pk_add_f32 v[234:235], v[234:235], s[100:101] op_sel_hi:[1,0]
	v_pk_add_f32 v[236:237], v[236:237], s[100:101] op_sel_hi:[1,0]
	v_pk_add_f32 v[238:239], v[238:239], s[100:101] op_sel_hi:[1,0]
	v_pk_add_f32 v[240:241], v[240:241], s[100:101] op_sel_hi:[1,0]
	v_rcp_f32_e32 v234, v234
	v_rcp_f32_e32 v235, v235
	v_rcp_f32_e32 v236, v236
	v_rcp_f32_e32 v237, v237
	v_rcp_f32_e32 v238, v238
	v_rcp_f32_e32 v239, v239
	v_rcp_f32_e32 v240, v240
	v_rcp_f32_e32 v241, v241
	v_pk_mul_f32 v[44:45], v[44:45], v[234:235]
	v_pk_mul_f32 v[46:47], v[46:47], v[236:237]
	v_pk_mul_f32 v[42:43], v[42:43], v[238:239]
	v_pk_mul_f32 v[40:41], v[40:41], v[240:241]
.LBB0_519:
	s_or_b64 exec, exec, s[26:27]
	v_cvt_pk_bf16_f32 v44, v44, v45
	v_cvt_pk_bf16_f32 v45, v46, v47
	v_cvt_pk_bf16_f32 v46, v40, v41
	v_cvt_pk_bf16_f32 v47, v42, v43
	global_store_dwordx4 v[104:105], v[44:47], off offset:256
	s_and_saveexec_b64 s[26:27], vcc
	s_cbranch_execz .LBB0_521
	v_pk_mul_f32 v[234:235], v[36:37], v[242:243] op_sel_hi:[1,0]
	v_pk_mul_f32 v[236:237], v[38:39], v[242:243] op_sel_hi:[1,0]
	v_pk_mul_f32 v[238:239], v[34:35], v[242:243] op_sel_hi:[1,0]
	v_pk_mul_f32 v[240:241], v[32:33], v[242:243] op_sel_hi:[1,0]
	v_pk_mul_f32 v[234:235], v[36:37], v[234:235]
	v_pk_mul_f32 v[236:237], v[38:39], v[236:237]
	v_pk_mul_f32 v[238:239], v[34:35], v[238:239]
	v_pk_mul_f32 v[240:241], v[32:33], v[240:241]
	v_pk_fma_f32 v[234:235], v[36:37], v[234:235], v[36:37]
	v_pk_fma_f32 v[236:237], v[38:39], v[236:237], v[38:39]
	v_pk_fma_f32 v[238:239], v[34:35], v[238:239], v[34:35]
	v_pk_fma_f32 v[240:241], v[32:33], v[240:241], v[32:33]
	v_pk_mul_f32 v[234:235], v[234:235], v[244:245] op_sel_hi:[1,0]
	v_pk_mul_f32 v[236:237], v[236:237], v[244:245] op_sel_hi:[1,0]
	v_pk_mul_f32 v[238:239], v[238:239], v[244:245] op_sel_hi:[1,0]
	v_pk_mul_f32 v[240:241], v[240:241], v[244:245] op_sel_hi:[1,0]
	v_pk_mul_f32 v[234:235], v[234:235], s[98:99] op_sel_hi:[1,0]
	v_pk_mul_f32 v[236:237], v[236:237], s[98:99] op_sel_hi:[1,0]
	v_pk_mul_f32 v[238:239], v[238:239], s[98:99] op_sel_hi:[1,0]
	v_pk_mul_f32 v[240:241], v[240:241], s[98:99] op_sel_hi:[1,0]
	v_exp_f32_e32 v234, v234
	v_exp_f32_e32 v235, v235
	v_exp_f32_e32 v236, v236
	v_exp_f32_e32 v237, v237
	v_exp_f32_e32 v238, v238
	v_exp_f32_e32 v239, v239
	v_exp_f32_e32 v240, v240
	v_exp_f32_e32 v241, v241
	v_pk_add_f32 v[234:235], v[234:235], s[100:101] op_sel_hi:[1,0]
	v_pk_add_f32 v[236:237], v[236:237], s[100:101] op_sel_hi:[1,0]
	v_pk_add_f32 v[238:239], v[238:239], s[100:101] op_sel_hi:[1,0]
	v_pk_add_f32 v[240:241], v[240:241], s[100:101] op_sel_hi:[1,0]
	v_rcp_f32_e32 v234, v234
	v_rcp_f32_e32 v235, v235
	v_rcp_f32_e32 v236, v236
	v_rcp_f32_e32 v237, v237
	v_rcp_f32_e32 v238, v238
	v_rcp_f32_e32 v239, v239
	v_rcp_f32_e32 v240, v240
	v_rcp_f32_e32 v241, v241
	v_pk_mul_f32 v[36:37], v[36:37], v[234:235]
	v_pk_mul_f32 v[38:39], v[38:39], v[236:237]
	v_pk_mul_f32 v[34:35], v[34:35], v[238:239]
	v_pk_mul_f32 v[32:33], v[32:33], v[240:241]
; __device__ __forceinline__ unsigned cvt_pk_bf16(float lo, float hi) { unsigned r; asm volatile("v_cvt_pk_bf16_f32 %0, %1, %2" : "=v"(r) : "v"(lo), "v"(hi)); return r; }
; __device__ __forceinline__ float bf_lo(unsigned w) { return __uint_as_float(w << 16); }
; __device__ __forceinline__ float bf_hi(unsigned w) { return __uint_as_float(w & 0xffff0000u); }
; __device__ __forceinline__ float sigmoid_f(float x) { return __builtin_amdgcn_rcpf(1.0f + __expf(-x)); }
; __device__ __forceinline__ float gelu_t(float x) { const float u = 1.5957691216057308f * (x + 0.044715f * x * x * x); return x * sigmoid_f(u); }
;     __device__ __forceinline__ void operator()(const f32x4 (&acc)[2][2][4][2], const Unit& u, int wr, int wc, int fr, int fq) const {
;     ...
;                 for (int m = 0; m < 4; ++m) {
;                     const size_t row = (size_t)(row0 + ai * HALF + m * 16);
;                     f32x4 v0 = acc[ai][bj][m][0], v1 = acc[ai][bj][m][1];
;                     if (MODE == 1) { if (act) {
; #pragma unroll
;                         for (int j = 0; j < 4; ++j) { v0[j] = gelu_t(v0[j]); v1[j] = gelu_t(v1[j]); } } }
;                     if (MODE == 2) {
;                         const u32x4 y = *(const u32x4*)(Y + row * ldy + col);
;                         v0 = v0 + b0; v1 = v1 + b1;
;                         v0[0] = bf_lo(y.x) * sigmoid_f(v0[0]); v0[1] = bf_hi(y.x) * sigmoid_f(v0[1]); v0[2] = bf_lo(y.y) * sigmoid_f(v0[2]); v0[3] = bf_hi(y.y) * sigmoid_f(v0[3]);
;                         v1[0] = bf_lo(y.z) * sigmoid_f(v1[0]); v1[1] = bf_hi(y.z) * sigmoid_f(v1[1]); v1[2] = bf_lo(y.w) * sigmoid_f(v1[2]); v1[3] = bf_hi(y.w) * sigmoid_f(v1[3]);
;                     }
;                     u32x4 w; w.x = cvt_pk_bf16(v0[0], v0[1]); w.y = cvt_pk_bf16(v0[2], v0[3]); w.z = cvt_pk_bf16(v1[0], v1[1]); w.w = cvt_pk_bf16(v1[2], v1[3]);
;                     *(u32x4*)(O + row * ldc + col) = w;
.LBB0_521:
	s_or_b64 exec, exec, s[26:27]
	v_cvt_pk_bf16_f32 v36, v36, v37
	v_cvt_pk_bf16_f32 v37, v38, v39
	v_cvt_pk_bf16_f32 v38, v32, v33
	v_cvt_pk_bf16_f32 v39, v34, v35
	global_store_dwordx4 v[96:97], v[36:39], off offset:256
	s_and_saveexec_b64 s[26:27], vcc
	s_cbranch_execz .LBB0_523
	v_pk_mul_f32 v[234:235], v[28:29], v[242:243] op_sel_hi:[1,0]
	v_pk_mul_f32 v[236:237], v[30:31], v[242:243] op_sel_hi:[1,0]
	v_pk_mul_f32 v[238:239], v[26:27], v[242:243] op_sel_hi:[1,0]
	v_pk_mul_f32 v[240:241], v[24:25], v[242:243] op_sel_hi:[1,0]
	v_pk_mul_f32 v[234:235], v[28:29], v[234:235]
	v_pk_mul_f32 v[236:237], v[30:31], v[236:237]
	v_pk_mul_f32 v[238:239], v[26:27], v[238:239]
	v_pk_mul_f32 v[240:241], v[24:25], v[240:241]
	v_pk_fma_f32 v[234:235], v[28:29], v[234:235], v[28:29]
	v_pk_fma_f32 v[236:237], v[30:31], v[236:237], v[30:31]
	v_pk_fma_f32 v[238:239], v[26:27], v[238:239], v[26:27]
	v_pk_fma_f32 v[240:241], v[24:25], v[240:241], v[24:25]
	v_pk_mul_f32 v[234:235], v[234:235], v[244:245] op_sel_hi:[1,0]
	v_pk_mul_f32 v[236:237], v[236:237], v[244:245] op_sel_hi:[1,0]
	v_pk_mul_f32 v[238:239], v[238:239], v[244:245] op_sel_hi:[1,0]
	v_pk_mul_f32 v[240:241], v[240:241], v[244:245] op_sel_hi:[1,0]
	v_pk_mul_f32 v[234:235], v[234:235], s[98:99] op_sel_hi:[1,0]
	v_pk_mul_f32 v[236:237], v[236:237], s[98:99] op_sel_hi:[1,0]
	v_pk_mul_f32 v[238:239], v[238:239], s[98:99] op_sel_hi:[1,0]
	v_pk_mul_f32 v[240:241], v[240:241], s[98:99] op_sel_hi:[1,0]
	v_exp_f32_e32 v234, v234
	v_exp_f32_e32 v235, v235
	v_exp_f32_e32 v236, v236
	v_exp_f32_e32 v237, v237
	v_exp_f32_e32 v238, v238
	v_exp_f32_e32 v239, v239
	v_exp_f32_e32 v240, v240
	v_exp_f32_e32 v241, v241
	v_pk_add_f32 v[234:235], v[234:235], s[100:101] op_sel_hi:[1,0]
	v_pk_add_f32 v[236:237], v[236:237], s[100:101] op_sel_hi:[1,0]
	v_pk_add_f32 v[238:239], v[238:239], s[100:101] op_sel_hi:[1,0]
	v_pk_add_f32 v[240:241], v[240:241], s[100:101] op_sel_hi:[1,0]
	v_rcp_f32_e32 v234, v234
	v_rcp_f32_e32 v235, v235
	v_rcp_f32_e32 v236, v236
	v_rcp_f32_e32 v237, v237
	v_rcp_f32_e32 v238, v238
	v_rcp_f32_e32 v239, v239
	v_rcp_f32_e32 v240, v240
	v_rcp_f32_e32 v241, v241
	v_pk_mul_f32 v[28:29], v[28:29], v[234:235]
	v_pk_mul_f32 v[30:31], v[30:31], v[236:237]
	v_pk_mul_f32 v[26:27], v[26:27], v[238:239]
	v_pk_mul_f32 v[24:25], v[24:25], v[240:241]
.LBB0_523:
	s_or_b64 exec, exec, s[26:27]
	v_cvt_pk_bf16_f32 v28, v28, v29
	v_cvt_pk_bf16_f32 v29, v30, v31
	v_cvt_pk_bf16_f32 v30, v24, v25
	v_cvt_pk_bf16_f32 v31, v26, v27
	global_store_dwordx4 v[88:89], v[28:31], off offset:256
	s_and_saveexec_b64 s[26:27], vcc
	s_cbranch_execz .LBB0_525
	v_pk_mul_f32 v[234:235], v[20:21], v[242:243] op_sel_hi:[1,0]
	v_pk_mul_f32 v[236:237], v[22:23], v[242:243] op_sel_hi:[1,0]
	v_pk_mul_f32 v[238:239], v[18:19], v[242:243] op_sel_hi:[1,0]
	v_pk_mul_f32 v[240:241], v[16:17], v[242:243] op_sel_hi:[1,0]
	v_pk_mul_f32 v[234:235], v[20:21], v[234:235]
	v_pk_mul_f32 v[236:237], v[22:23], v[236:237]
	v_pk_mul_f32 v[238:239], v[18:19], v[238:239]
	v_pk_mul_f32 v[240:241], v[16:17], v[240:241]
	v_pk_fma_f32 v[234:235], v[20:21], v[234:235], v[20:21]
	v_pk_fma_f32 v[236:237], v[22:23], v[236:237], v[22:23]
	v_pk_fma_f32 v[238:239], v[18:19], v[238:239], v[18:19]
	v_pk_fma_f32 v[240:241], v[16:17], v[240:241], v[16:17]
	v_pk_mul_f32 v[234:235], v[234:235], v[244:245] op_sel_hi:[1,0]
	v_pk_mul_f32 v[236:237], v[236:237], v[244:245] op_sel_hi:[1,0]
	v_pk_mul_f32 v[238:239], v[238:239], v[244:245] op_sel_hi:[1,0]
	v_pk_mul_f32 v[240:241], v[240:241], v[244:245] op_sel_hi:[1,0]
	v_pk_mul_f32 v[234:235], v[234:235], s[98:99] op_sel_hi:[1,0]
	v_pk_mul_f32 v[236:237], v[236:237], s[98:99] op_sel_hi:[1,0]
	v_pk_mul_f32 v[238:239], v[238:239], s[98:99] op_sel_hi:[1,0]
	v_pk_mul_f32 v[240:241], v[240:241], s[98:99] op_sel_hi:[1,0]
	v_exp_f32_e32 v234, v234
	v_exp_f32_e32 v235, v235
	v_exp_f32_e32 v236, v236
	v_exp_f32_e32 v237, v237
	v_exp_f32_e32 v238, v238
	v_exp_f32_e32 v239, v239
	v_exp_f32_e32 v240, v240
	v_exp_f32_e32 v241, v241
	v_pk_add_f32 v[234:235], v[234:235], s[100:101] op_sel_hi:[1,0]
	v_pk_add_f32 v[236:237], v[236:237], s[100:101] op_sel_hi:[1,0]
	v_pk_add_f32 v[238:239], v[238:239], s[100:101] op_sel_hi:[1,0]
	v_pk_add_f32 v[240:241], v[240:241], s[100:101] op_sel_hi:[1,0]
	v_rcp_f32_e32 v234, v234
	v_rcp_f32_e32 v235, v235
	v_rcp_f32_e32 v236, v236
	v_rcp_f32_e32 v237, v237
	v_rcp_f32_e32 v238, v238
	v_rcp_f32_e32 v239, v239
	v_rcp_f32_e32 v240, v240
	v_rcp_f32_e32 v241, v241
	v_pk_mul_f32 v[20:21], v[20:21], v[234:235]
	v_pk_mul_f32 v[22:23], v[22:23], v[236:237]
	v_pk_mul_f32 v[18:19], v[18:19], v[238:239]
	v_pk_mul_f32 v[16:17], v[16:17], v[240:241]
; __device__ __forceinline__ unsigned cvt_pk_bf16(float lo, float hi) { unsigned r; asm volatile("v_cvt_pk_bf16_f32 %0, %1, %2" : "=v"(r) : "v"(lo), "v"(hi)); return r; }
; __device__ __forceinline__ float bf_lo(unsigned w) { return __uint_as_float(w << 16); }
; __device__ __forceinline__ float bf_hi(unsigned w) { return __uint_as_float(w & 0xffff0000u); }
; __device__ __forceinline__ float sigmoid_f(float x) { return __builtin_amdgcn_rcpf(1.0f + __expf(-x)); }
; __device__ __forceinline__ float gelu_t(float x) { const float u = 1.5957691216057308f * (x + 0.044715f * x * x * x); return x * sigmoid_f(u); }
;     __device__ __forceinline__ void operator()(const f32x4 (&acc)[2][2][4][2], const Unit& u, int wr, int wc, int fr, int fq) const {
;     ...
;                 for (int m = 0; m < 4; ++m) {
;                     const size_t row = (size_t)(row0 + ai * HALF + m * 16);
;                     f32x4 v0 = acc[ai][bj][m][0], v1 = acc[ai][bj][m][1];
;                     if (MODE == 1) { if (act) {
; #pragma unroll
;                         for (int j = 0; j < 4; ++j) { v0[j] = gelu_t(v0[j]); v1[j] = gelu_t(v1[j]); } } }
;                     if (MODE == 2) {
;                         const u32x4 y = *(const u32x4*)(Y + row * ldy + col);
;                         v0 = v0 + b0; v1 = v1 + b1;
;                         v0[0] = bf_lo(y.x) * sigmoid_f(v0[0]); v0[1] = bf_hi(y.x) * sigmoid_f(v0[1]); v0[2] = bf_lo(y.y) * sigmoid_f(v0[2]); v0[3] = bf_hi(y.y) * sigmoid_f(v0[3]);
;                         v1[0] = bf_lo(y.z) * sigmoid_f(v1[0]); v1[1] = bf_hi(y.z) * sigmoid_f(v1[1]); v1[2] = bf_lo(y.w) * sigmoid_f(v1[2]); v1[3] = bf_hi(y.w) * sigmoid_f(v1[3]);
;                     }
;                     u32x4 w; w.x = cvt_pk_bf16(v0[0], v0[1]); w.y = cvt_pk_bf16(v0[2], v0[3]); w.z = cvt_pk_bf16(v1[0], v1[1]); w.w = cvt_pk_bf16(v1[2], v1[3]);
;                     *(u32x4*)(O + row * ldc + col) = w;
.LBB0_525:
	s_or_b64 exec, exec, s[26:27]
	v_cvt_pk_bf16_f32 v20, v20, v21
	v_cvt_pk_bf16_f32 v21, v22, v23
	v_cvt_pk_bf16_f32 v22, v16, v17
	v_cvt_pk_bf16_f32 v23, v18, v19
	global_store_dwordx4 v[80:81], v[20:23], off offset:256
	s_and_saveexec_b64 s[26:27], vcc
	s_cbranch_execz .LBB0_527
	v_pk_mul_f32 v[234:235], v[12:13], v[242:243] op_sel_hi:[1,0]
	v_pk_mul_f32 v[236:237], v[14:15], v[242:243] op_sel_hi:[1,0]
	v_pk_mul_f32 v[238:239], v[10:11], v[242:243] op_sel_hi:[1,0]
	v_pk_mul_f32 v[240:241], v[8:9], v[242:243] op_sel_hi:[1,0]
	v_pk_mul_f32 v[234:235], v[12:13], v[234:235]
	v_pk_mul_f32 v[236:237], v[14:15], v[236:237]
	v_pk_mul_f32 v[238:239], v[10:11], v[238:239]
	v_pk_mul_f32 v[240:241], v[8:9], v[240:241]
	v_pk_fma_f32 v[234:235], v[12:13], v[234:235], v[12:13]
	v_pk_fma_f32 v[236:237], v[14:15], v[236:237], v[14:15]
	v_pk_fma_f32 v[238:239], v[10:11], v[238:239], v[10:11]
	v_pk_fma_f32 v[240:241], v[8:9], v[240:241], v[8:9]
	v_pk_mul_f32 v[234:235], v[234:235], v[244:245] op_sel_hi:[1,0]
	v_pk_mul_f32 v[236:237], v[236:237], v[244:245] op_sel_hi:[1,0]
	v_pk_mul_f32 v[238:239], v[238:239], v[244:245] op_sel_hi:[1,0]
	v_pk_mul_f32 v[240:241], v[240:241], v[244:245] op_sel_hi:[1,0]
	v_pk_mul_f32 v[234:235], v[234:235], s[98:99] op_sel_hi:[1,0]
	v_pk_mul_f32 v[236:237], v[236:237], s[98:99] op_sel_hi:[1,0]
	v_pk_mul_f32 v[238:239], v[238:239], s[98:99] op_sel_hi:[1,0]
	v_pk_mul_f32 v[240:241], v[240:241], s[98:99] op_sel_hi:[1,0]
	v_exp_f32_e32 v234, v234
	v_exp_f32_e32 v235, v235
	v_exp_f32_e32 v236, v236
	v_exp_f32_e32 v237, v237
	v_exp_f32_e32 v238, v238
	v_exp_f32_e32 v239, v239
	v_exp_f32_e32 v240, v240
	v_exp_f32_e32 v241, v241
	v_pk_add_f32 v[234:235], v[234:235], s[100:101] op_sel_hi:[1,0]
	v_pk_add_f32 v[236:237], v[236:237], s[100:101] op_sel_hi:[1,0]
	v_pk_add_f32 v[238:239], v[238:239], s[100:101] op_sel_hi:[1,0]
	v_pk_add_f32 v[240:241], v[240:241], s[100:101] op_sel_hi:[1,0]
	v_rcp_f32_e32 v234, v234
	v_rcp_f32_e32 v235, v235
	v_rcp_f32_e32 v236, v236
	v_rcp_f32_e32 v237, v237
	v_rcp_f32_e32 v238, v238
	v_rcp_f32_e32 v239, v239
	v_rcp_f32_e32 v240, v240
	v_rcp_f32_e32 v241, v241
	v_pk_mul_f32 v[12:13], v[12:13], v[234:235]
	v_pk_mul_f32 v[14:15], v[14:15], v[236:237]
	v_pk_mul_f32 v[10:11], v[10:11], v[238:239]
	v_pk_mul_f32 v[8:9], v[8:9], v[240:241]
.LBB0_527:
	s_or_b64 exec, exec, s[26:27]
	v_cvt_pk_bf16_f32 v12, v12, v13
	v_cvt_pk_bf16_f32 v13, v14, v15
	v_cvt_pk_bf16_f32 v14, v8, v9
	v_cvt_pk_bf16_f32 v15, v10, v11
	global_store_dwordx4 v[72:73], v[12:15], off offset:256
	s_and_saveexec_b64 s[26:27], vcc
	s_cbranch_execz .LBB0_529
	v_pk_mul_f32 v[234:235], v[4:5], v[242:243] op_sel_hi:[1,0]
	v_pk_mul_f32 v[236:237], v[6:7], v[242:243] op_sel_hi:[1,0]
	v_pk_mul_f32 v[238:239], v[2:3], v[242:243] op_sel_hi:[1,0]
	v_pk_mul_f32 v[240:241], v[0:1], v[242:243] op_sel_hi:[1,0]
	v_pk_mul_f32 v[234:235], v[4:5], v[234:235]
	v_pk_mul_f32 v[236:237], v[6:7], v[236:237]
	v_pk_mul_f32 v[238:239], v[2:3], v[238:239]
	v_pk_mul_f32 v[240:241], v[0:1], v[240:241]
	v_pk_fma_f32 v[234:235], v[4:5], v[234:235], v[4:5]
	v_pk_fma_f32 v[236:237], v[6:7], v[236:237], v[6:7]
	v_pk_fma_f32 v[238:239], v[2:3], v[238:239], v[2:3]
	v_pk_fma_f32 v[240:241], v[0:1], v[240:241], v[0:1]
	v_pk_mul_f32 v[234:235], v[234:235], v[244:245] op_sel_hi:[1,0]
	v_pk_mul_f32 v[236:237], v[236:237], v[244:245] op_sel_hi:[1,0]
	v_pk_mul_f32 v[238:239], v[238:239], v[244:245] op_sel_hi:[1,0]
	v_pk_mul_f32 v[240:241], v[240:241], v[244:245] op_sel_hi:[1,0]
	v_pk_mul_f32 v[234:235], v[234:235], s[98:99] op_sel_hi:[1,0]
	v_pk_mul_f32 v[236:237], v[236:237], s[98:99] op_sel_hi:[1,0]
	v_pk_mul_f32 v[238:239], v[238:239], s[98:99] op_sel_hi:[1,0]
	v_pk_mul_f32 v[240:241], v[240:241], s[98:99] op_sel_hi:[1,0]
	v_exp_f32_e32 v234, v234
	v_exp_f32_e32 v235, v235
	v_exp_f32_e32 v236, v236
	v_exp_f32_e32 v237, v237
	v_exp_f32_e32 v238, v238
	v_exp_f32_e32 v239, v239
	v_exp_f32_e32 v240, v240
	v_exp_f32_e32 v241, v241
	v_pk_add_f32 v[234:235], v[234:235], s[100:101] op_sel_hi:[1,0]
	v_pk_add_f32 v[236:237], v[236:237], s[100:101] op_sel_hi:[1,0]
	v_pk_add_f32 v[238:239], v[238:239], s[100:101] op_sel_hi:[1,0]
	v_pk_add_f32 v[240:241], v[240:241], s[100:101] op_sel_hi:[1,0]
	v_rcp_f32_e32 v234, v234
	v_rcp_f32_e32 v235, v235
	v_rcp_f32_e32 v236, v236
	v_rcp_f32_e32 v237, v237
	v_rcp_f32_e32 v238, v238
	v_rcp_f32_e32 v239, v239
	v_rcp_f32_e32 v240, v240
	v_rcp_f32_e32 v241, v241
	v_pk_mul_f32 v[4:5], v[4:5], v[234:235]
	v_pk_mul_f32 v[6:7], v[6:7], v[236:237]
	v_pk_mul_f32 v[2:3], v[2:3], v[238:239]
	v_pk_mul_f32 v[0:1], v[0:1], v[240:241]

; #define LAS __attribute__((address_space(3)))
; template <bool PASS2>
; __device__ __forceinline__ void s5_tile(const Ctx& C, int T, int sb_lo, int sb_hi, LAS unsigned char* lds, int wave, int lane) {
;     ...
;         for (int gi = 0; gi < 4; ++gi) {
;             const int g = wave * 4 + gi, gnx = wave * 4 + ((gi + 1) & 3);
;             bfx8 bb[4], cm[4];
; #pragma unroll
;             for (int cb = 0; cb < 4; ++cb) { bb[cb] = bbn[cb]; bbn[cb] = *(const bfx8*)(BBt + ((size_t)(gnx * 128 + cb * 32 + tl)) * GN + 8 * hh); }
;             if (PASS2) {
; #pragma unroll
;                 for (int ks = 0; ks < 4; ++ks) { cm[ks] = cmn[ks]; cmn[ks] = *(const bfx8*)(CMt + ((size_t)(gnx * GN + fr)) * 128 + 32 * ks + 8 * kq); }
;             }
;             float s0ar = 0.f, s0ai = 0.f, s0br = 0.f, s0bi = 0.f;
;             if (sample) { const size_t o0 = ((size_t)(2 * sb) * NG + g) * NP + lane, o1 = o0 + (size_t)NG * NP;
;                 s0ar = C.in(2)[o0]; s0ai = C.in(3)[o0]; s0br = C.in(2)[o1]; s0bi = C.in(3)[o1]; }
;             const bfx8 a = *(const LAS bfx8*)(XU + tl * XU_STRIDE + 16 * gi + 8 * hh);
; #pragma unroll
;             for (int cb = 0; cb < 4; ++cb) {
;                 v16f acc;
; #pragma unroll
;                 for (int r = 0; r < 16; ++r) acc[r] = 0.f;
;                 acc = __builtin_amdgcn_mfma_f32_32x32x16_bf16(bb[cb], a, acc, 0, 0, 0);
; #pragma unroll
;                 for (int rg = 0; rg < 4; ++rg) { v2u w; w.x = cvt_pk_c(acc[4 * rg], acc[4 * rg + 1]); w.y = cvt_pk_c(acc[4 * rg + 2], acc[4 * rg + 3]);
;                     *(LAS v2u*)(BH + tl * BH_STRIDE + cb * 32 + 8 * rg + 4 * hh) = w; }
;             }
;             LDS_FENCE();
;             {
;                 unsigned bu[32];
; #pragma unroll
;                 for (int t = 0; t < 32; ++t) bu[t] = *(const LAS unsigned*)(BH + t * BH_STRIDE + 2 * lane);
;                 LDS_FENCE();
;                 float xr = sr[gi], xi = si[gi];
; #pragma unroll
;                 for (int t = 0; t < 32; ++t) {
;                     if (sample && t == 0) { xr = s0ar; xi = s0ai; }
;                     if (sample && t == 16) { xr = s0br; xi = s0bi; }
;                     const float nr = fmaf(lr[gi], xr, fmaf(-li[gi], xi, bf_lo(bu[t]))), ni = fmaf(lr[gi], xi, fmaf(li[gi], xr, bf_hi(bu[t])));
;                     xr = nr; xi = ni;
;                     if (PASS2) {
.LBB0_666:
	s_waitcnt lgkmcnt(0)
	global_load_dwordx4 v[92:95], v[126:127], off
	global_load_dwordx4 v[88:91], v[128:129], off
	global_load_dwordx4 v[84:87], v[130:131], off
	global_load_dwordx4 v[80:83], v[132:133], off
	ds_read_b128 v[250:253], v192
	global_load_dwordx4 v[60:63], v[134:135], off
	global_load_dwordx4 v[56:59], v[134:135], off offset:1024
	global_load_dwordx4 v[48:51], v[134:135], off offset:2048
	global_load_dwordx4 v[52:55], v[134:135], off offset:3072
	s_waitcnt vmcnt(8) lgkmcnt(0)
	v_mfma_f32_32x32x16_bf16 v[0:15], v[250:253], v[76:79], 0
	v_mfma_f32_32x32x16_bf16 v[214:229], v[250:253], v[72:75], 0
	s_mov_b64 s[0:1], s[80:81]
	s_add_i32 s14, s14, 32
	s_add_i32 s15, s15, 1
	s_cmpk_eq_i32 s15, 4
	v_mfma_f32_32x32x16_bf16 v[234:249], v[250:253], v[68:71], 0
	v_mfma_f32_32x32x16_bf16 v[198:213], v[250:253], v[64:67], 0
	s_nop 11
	v_permlane32_swap_b32_e32 v0, v234
	v_permlane32_swap_b32_e32 v1, v235
	v_permlane32_swap_b32_e32 v2, v236
	v_permlane32_swap_b32_e32 v3, v237
	v_permlane32_swap_b32_e32 v4, v238
	v_permlane32_swap_b32_e32 v5, v239
	v_permlane32_swap_b32_e32 v6, v240
	v_permlane32_swap_b32_e32 v7, v241
	v_permlane32_swap_b32_e32 v8, v242
	v_permlane32_swap_b32_e32 v9, v243
	v_permlane32_swap_b32_e32 v10, v244
	v_permlane32_swap_b32_e32 v11, v245
	v_permlane32_swap_b32_e32 v12, v246
	v_permlane32_swap_b32_e32 v13, v247
	v_permlane32_swap_b32_e32 v14, v248
	v_permlane32_swap_b32_e32 v15, v249
	v_permlane32_swap_b32_e32 v214, v198
	v_permlane32_swap_b32_e32 v215, v199
	v_permlane32_swap_b32_e32 v216, v200
	v_permlane32_swap_b32_e32 v217, v201
	v_permlane32_swap_b32_e32 v218, v202
	v_permlane32_swap_b32_e32 v219, v203
	v_permlane32_swap_b32_e32 v220, v204
	v_permlane32_swap_b32_e32 v221, v205
	v_permlane32_swap_b32_e32 v222, v206
	v_permlane32_swap_b32_e32 v223, v207
	v_permlane32_swap_b32_e32 v224, v208
	v_permlane32_swap_b32_e32 v225, v209
	v_permlane32_swap_b32_e32 v226, v210
	v_permlane32_swap_b32_e32 v227, v211
	v_permlane32_swap_b32_e32 v228, v212
	v_permlane32_swap_b32_e32 v229, v213
	v_fma_f32 v0, -v174, v112, v0
	v_fma_f32 v214, v174, v114, v214
	v_fma_f32 v114, v173, v114, v0
	v_fma_f32 v112, v173, v112, v214
	v_cvt_pk_bf16_f32 v197, v114, v112
	ds_write_b32 v107, v197 offset:4608
	v_fma_f32 v1, -v174, v112, v1
	v_fma_f32 v215, v174, v114, v215
	v_fma_f32 v114, v173, v114, v1
	v_fma_f32 v112, v173, v112, v215
	v_cvt_pk_bf16_f32 v197, v114, v112
	ds_write_b32 v107, v197 offset:4880
	v_fma_f32 v2, -v174, v112, v2
	v_fma_f32 v216, v174, v114, v216
	v_fma_f32 v114, v173, v114, v2
	v_fma_f32 v112, v173, v112, v216
	v_cvt_pk_bf16_f32 v197, v114, v112
	ds_write_b32 v107, v197 offset:5152
	v_fma_f32 v3, -v174, v112, v3
	v_fma_f32 v217, v174, v114, v217
	v_fma_f32 v114, v173, v114, v3
	v_fma_f32 v112, v173, v112, v217
	v_cvt_pk_bf16_f32 v197, v114, v112
	ds_write_b32 v107, v197 offset:5424
	v_fma_f32 v234, -v174, v112, v234
	v_fma_f32 v198, v174, v114, v198
	v_fma_f32 v114, v173, v114, v234
	v_fma_f32 v112, v173, v112, v198
	v_cvt_pk_bf16_f32 v197, v114, v112
	ds_write_b32 v107, v197 offset:5696
	v_fma_f32 v235, -v174, v112, v235
	v_fma_f32 v199, v174, v114, v199
	v_fma_f32 v114, v173, v114, v235
	v_fma_f32 v112, v173, v112, v199
	v_cvt_pk_bf16_f32 v197, v114, v112
	ds_write_b32 v107, v197 offset:5968
	v_fma_f32 v236, -v174, v112, v236
	v_fma_f32 v200, v174, v114, v200
	v_fma_f32 v114, v173, v114, v236
	v_fma_f32 v112, v173, v112, v200
	v_cvt_pk_bf16_f32 v197, v114, v112
	ds_write_b32 v107, v197 offset:6240
	v_fma_f32 v237, -v174, v112, v237
	v_fma_f32 v201, v174, v114, v201
	v_fma_f32 v114, v173, v114, v237
	v_fma_f32 v112, v173, v112, v201
	v_cvt_pk_bf16_f32 v197, v114, v112
	ds_write_b32 v107, v197 offset:6512
	v_fma_f32 v4, -v174, v112, v4
	v_fma_f32 v218, v174, v114, v218
	v_fma_f32 v114, v173, v114, v4
	v_fma_f32 v112, v173, v112, v218
	v_cvt_pk_bf16_f32 v197, v114, v112
	ds_write_b32 v107, v197 offset:6784
	v_fma_f32 v5, -v174, v112, v5
	v_fma_f32 v219, v174, v114, v219
	v_fma_f32 v114, v173, v114, v5
	v_fma_f32 v112, v173, v112, v219
	v_cvt_pk_bf16_f32 v197, v114, v112
	ds_write_b32 v107, v197 offset:7056
	v_fma_f32 v6, -v174, v112, v6
	v_fma_f32 v220, v174, v114, v220
	v_fma_f32 v114, v173, v114, v6
	v_fma_f32 v112, v173, v112, v220
	v_cvt_pk_bf16_f32 v197, v114, v112
	ds_write_b32 v107, v197 offset:7328
	v_fma_f32 v7, -v174, v112, v7
	v_fma_f32 v221, v174, v114, v221
	v_fma_f32 v114, v173, v114, v7
	v_fma_f32 v112, v173, v112, v221
	v_cvt_pk_bf16_f32 v197, v114, v112
	ds_write_b32 v107, v197 offset:7600
	v_fma_f32 v238, -v174, v112, v238
	v_fma_f32 v202, v174, v114, v202
	v_fma_f32 v114, v173, v114, v238
	v_fma_f32 v112, v173, v112, v202
	v_cvt_pk_bf16_f32 v197, v114, v112
	ds_write_b32 v107, v197 offset:7872
	v_fma_f32 v239, -v174, v112, v239
	v_fma_f32 v203, v174, v114, v203
	v_fma_f32 v114, v173, v114, v239
	v_fma_f32 v112, v173, v112, v203
	v_cvt_pk_bf16_f32 v197, v114, v112
	ds_write_b32 v107, v197 offset:8144
	v_fma_f32 v240, -v174, v112, v240
	v_fma_f32 v204, v174, v114, v204
	v_fma_f32 v114, v173, v114, v240
	v_fma_f32 v112, v173, v112, v204
	v_cvt_pk_bf16_f32 v197, v114, v112
	ds_write_b32 v107, v197 offset:8416
	v_fma_f32 v241, -v174, v112, v241
	v_fma_f32 v205, v174, v114, v205
	v_fma_f32 v114, v173, v114, v241
	v_fma_f32 v112, v173, v112, v205
	v_cvt_pk_bf16_f32 v197, v114, v112
	ds_write_b32 v107, v197 offset:8688
	v_fma_f32 v8, -v174, v112, v8
	v_fma_f32 v222, v174, v114, v222
	v_fma_f32 v114, v173, v114, v8
	v_fma_f32 v112, v173, v112, v222
	v_cvt_pk_bf16_f32 v197, v114, v112
	ds_write_b32 v107, v197 offset:8960
	v_fma_f32 v9, -v174, v112, v9
	v_fma_f32 v223, v174, v114, v223
; __device__ __forceinline__ float bf_lo(unsigned w) { return __uint_as_float(w << 16); }
; __device__ __forceinline__ float bf_hi(unsigned w) { return __uint_as_float(w & 0xffff0000u); }
; #define LAS __attribute__((address_space(3)))
; #define LDS_FENCE() asm volatile("s_waitcnt lgkmcnt(0)" ::: "memory")
;     __device__ __forceinline__ float* out() const { return (float*)karg_in(33); }
; template <bool PASS2>
; __device__ __forceinline__ void s5_tile(const Ctx& C, int T, int sb_lo, int sb_hi, LAS unsigned char* lds, int wave, int lane) {
;     ...
;                 for (int t = 0; t < 32; ++t) bu[t] = *(const LAS unsigned*)(BH + t * BH_STRIDE + 2 * lane);
;                 LDS_FENCE();
;                 float xr = sr[gi], xi = si[gi];
; #pragma unroll
;                 for (int t = 0; t < 32; ++t) {
;                     if (sample && t == 0) { xr = s0ar; xi = s0ai; }
;                     if (sample && t == 16) { xr = s0br; xi = s0bi; }
;                     const float nr = fmaf(lr[gi], xr, fmaf(-li[gi], xi, bf_lo(bu[t]))), ni = fmaf(lr[gi], xi, fmaf(li[gi], xr, bf_hi(bu[t])));
;                     xr = nr; xi = ni;
;                     if (PASS2) {
;                         *(LAS unsigned*)(BH + t * BH_STRIDE + 2 * lane) = cvt_pk_nv(xr, xi);
;                         if (sample && (t & 15) == 15) { const int seq = 2 * sb + (t >> 4);
;                             C.out()[OFF_SRE_S + ((size_t)seq * NG + g) * NP + lane] = xr; C.out()[OFF_SIM_S + ((size_t)seq * NG + g) * NP + lane] = xi; }
;                     }
;                 }
;                 sr[gi] = xr; si[gi] = xi;
;             }
;             LDS_FENCE();
;             if (PASS2) {
; #pragma unroll
;                 for (int rb = 0; rb < 2; ++rb) {
;                     v4f acc = (v4f){0.f, 0.f, 0.f, 0.f};
; #pragma unroll
;                     for (int ks = 0; ks < 4; ++ks) {
;                         const bfx8 sa = *(const LAS bfx8*)(BH + (16 * rb + fr) * BH_STRIDE + 32 * ks + 8 * kq);
;                         acc = __builtin_amdgcn_mfma_f32_16x16x32_bf16(sa, cm[ks], acc, 0, 0, 0);
;                     }
; #pragma unroll
;                     for (int r = 0; r < 4; ++r) {
;                         LAS bf16* up = XU + (16 * rb + 4 * kq + r) * XU_STRIDE + 16 * gi + fr;
;                         const float u = __uint_as_float((unsigned)(*up) << 16);
	v_fma_f32 v114, v173, v114, v9
	v_fma_f32 v112, v173, v112, v223
	v_cvt_pk_bf16_f32 v197, v114, v112
	ds_write_b32 v107, v197 offset:9232
	v_fma_f32 v10, -v174, v112, v10
	v_fma_f32 v224, v174, v114, v224
	v_fma_f32 v114, v173, v114, v10
	v_fma_f32 v112, v173, v112, v224
	v_cvt_pk_bf16_f32 v197, v114, v112
	ds_write_b32 v107, v197 offset:9504
	v_fma_f32 v11, -v174, v112, v11
	v_fma_f32 v225, v174, v114, v225
	v_fma_f32 v114, v173, v114, v11
	v_fma_f32 v112, v173, v112, v225
	v_cvt_pk_bf16_f32 v197, v114, v112
	ds_write_b32 v107, v197 offset:9776
	v_fma_f32 v242, -v174, v112, v242
	v_fma_f32 v206, v174, v114, v206
	v_fma_f32 v114, v173, v114, v242
	v_fma_f32 v112, v173, v112, v206
	v_cvt_pk_bf16_f32 v197, v114, v112
	ds_write_b32 v107, v197 offset:10048
	v_fma_f32 v243, -v174, v112, v243
	v_fma_f32 v207, v174, v114, v207
	v_fma_f32 v114, v173, v114, v243
	v_fma_f32 v112, v173, v112, v207
	v_cvt_pk_bf16_f32 v197, v114, v112
	ds_write_b32 v107, v197 offset:10320
	v_fma_f32 v244, -v174, v112, v244
	v_fma_f32 v208, v174, v114, v208
	v_fma_f32 v114, v173, v114, v244
	v_fma_f32 v112, v173, v112, v208
	v_cvt_pk_bf16_f32 v197, v114, v112
	ds_write_b32 v107, v197 offset:10592
	v_fma_f32 v245, -v174, v112, v245
	v_fma_f32 v209, v174, v114, v209
	v_fma_f32 v114, v173, v114, v245
	v_fma_f32 v112, v173, v112, v209
	v_cvt_pk_bf16_f32 v197, v114, v112
	ds_write_b32 v107, v197 offset:10864
	v_fma_f32 v12, -v174, v112, v12
	v_fma_f32 v226, v174, v114, v226
	v_fma_f32 v114, v173, v114, v12
	v_fma_f32 v112, v173, v112, v226
	v_cvt_pk_bf16_f32 v197, v114, v112
	ds_write_b32 v107, v197 offset:11136
	v_fma_f32 v13, -v174, v112, v13
	v_fma_f32 v227, v174, v114, v227
	v_fma_f32 v114, v173, v114, v13
	v_fma_f32 v112, v173, v112, v227
	v_cvt_pk_bf16_f32 v197, v114, v112
	ds_write_b32 v107, v197 offset:11408
	v_fma_f32 v14, -v174, v112, v14
	v_fma_f32 v228, v174, v114, v228
	v_fma_f32 v114, v173, v114, v14
	v_fma_f32 v112, v173, v112, v228
	v_cvt_pk_bf16_f32 v197, v114, v112
	ds_write_b32 v107, v197 offset:11680
	v_fma_f32 v15, -v174, v112, v15
	v_fma_f32 v229, v174, v114, v229
	v_fma_f32 v114, v173, v114, v15
	v_fma_f32 v112, v173, v112, v229
	v_cvt_pk_bf16_f32 v197, v114, v112
	ds_write_b32 v107, v197 offset:11952
	v_fma_f32 v246, -v174, v112, v246
	v_fma_f32 v210, v174, v114, v210
	v_fma_f32 v114, v173, v114, v246
	v_fma_f32 v112, v173, v112, v210
	v_cvt_pk_bf16_f32 v197, v114, v112
	ds_write_b32 v107, v197 offset:12224
	v_fma_f32 v247, -v174, v112, v247
	v_fma_f32 v211, v174, v114, v211
	v_fma_f32 v114, v173, v114, v247
	v_fma_f32 v112, v173, v112, v211
	v_cvt_pk_bf16_f32 v197, v114, v112
	ds_write_b32 v107, v197 offset:12496
	v_fma_f32 v248, -v174, v112, v248
	v_fma_f32 v212, v174, v114, v212
	v_fma_f32 v114, v173, v114, v248
	v_fma_f32 v112, v173, v112, v212
	v_cvt_pk_bf16_f32 v197, v114, v112
	ds_write_b32 v107, v197 offset:12768
	v_fma_f32 v249, -v174, v112, v249
	v_fma_f32 v213, v174, v114, v213
	v_fma_f32 v114, v173, v114, v249
	v_fma_f32 v112, v173, v112, v213
	v_cvt_pk_bf16_f32 v197, v114, v112
	ds_write_b32 v107, v197 offset:13040
	s_waitcnt lgkmcnt(0)
	ds_read_b128 v[214:217], v194 offset:4608
	ds_read_b128 v[218:221], v194 offset:4672
	ds_read_b128 v[222:225], v194 offset:4736
	ds_read_b128 v[226:229], v194 offset:4800
	ds_read_b128 v[234:237], v194 offset:8960
	ds_read_b128 v[238:241], v194 offset:9024
	ds_read_b128 v[242:245], v194 offset:9088
	ds_read_b128 v[246:249], v194 offset:9152
	ds_read_u16 v8, v195
	ds_read_u16 v9, v195 offset:144
	ds_read_u16 v10, v195 offset:288
	ds_read_u16 v11, v195 offset:432
	ds_read_u16 v12, v195 offset:2304
	ds_read_u16 v13, v195 offset:2448
	ds_read_u16 v14, v195 offset:2592
	ds_read_u16 v15, v195 offset:2736
	s_waitcnt lgkmcnt(8)
	v_mfma_f32_16x16x32_bf16 v[0:3], v[214:217], v[44:47], 0
	v_mfma_f32_16x16x32_bf16 v[4:7], v[234:237], v[44:47], 0
	v_mfma_f32_16x16x32_bf16 v[0:3], v[218:221], v[40:43], v[0:3]
	v_mfma_f32_16x16x32_bf16 v[4:7], v[238:241], v[40:43], v[4:7]
	v_mfma_f32_16x16x32_bf16 v[0:3], v[222:225], v[36:39], v[0:3]
	v_mfma_f32_16x16x32_bf16 v[4:7], v[242:245], v[36:39], v[4:7]
	v_mfma_f32_16x16x32_bf16 v[0:3], v[226:229], v[32:35], v[0:3]
	v_mfma_f32_16x16x32_bf16 v[4:7], v[246:249], v[32:35], v[4:7]
	s_waitcnt lgkmcnt(0)
; #define LAS __attribute__((address_space(3)))
; template <bool PASS2>
; __device__ __forceinline__ void s5_tile(const Ctx& C, int T, int sb_lo, int sb_hi, LAS unsigned char* lds, int wave, int lane) {
;     ...
;         for (int gi = 0; gi < 4; ++gi) {
;             const int g = wave * 4 + gi, gnx = wave * 4 + ((gi + 1) & 3);
;             bfx8 bb[4], cm[4];
; #pragma unroll
;             for (int cb = 0; cb < 4; ++cb) { bb[cb] = bbn[cb]; bbn[cb] = *(const bfx8*)(BBt + ((size_t)(gnx * 128 + cb * 32 + tl)) * GN + 8 * hh); }
;             if (PASS2) {
; #pragma unroll
;                 for (int ks = 0; ks < 4; ++ks) { cm[ks] = cmn[ks]; cmn[ks] = *(const bfx8*)(CMt + ((size_t)(gnx * GN + fr)) * 128 + 32 * ks + 8 * kq); }
;             }
;             float s0ar = 0.f, s0ai = 0.f, s0br = 0.f, s0bi = 0.f;
;             if (sample) { const size_t o0 = ((size_t)(2 * sb) * NG + g) * NP + lane, o1 = o0 + (size_t)NG * NP;
;                 s0ar = C.in(2)[o0]; s0ai = C.in(3)[o0]; s0br = C.in(2)[o1]; s0bi = C.in(3)[o1]; }
;             const bfx8 a = *(const LAS bfx8*)(XU + tl * XU_STRIDE + 16 * gi + 8 * hh);
; #pragma unroll
;             for (int cb = 0; cb < 4; ++cb) {
;                 v16f acc;
; #pragma unroll
;                 for (int r = 0; r < 16; ++r) acc[r] = 0.f;
;                 acc = __builtin_amdgcn_mfma_f32_32x32x16_bf16(bb[cb], a, acc, 0, 0, 0);
; #pragma unroll
;                 for (int rg = 0; rg < 4; ++rg) { v2u w; w.x = cvt_pk_c(acc[4 * rg], acc[4 * rg + 1]); w.y = cvt_pk_c(acc[4 * rg + 2], acc[4 * rg + 3]);
;                     *(LAS v2u*)(BH + tl * BH_STRIDE + cb * 32 + 8 * rg + 4 * hh) = w; }
;             }
;             LDS_FENCE();
;             {
;                 unsigned bu[32];
; #pragma unroll
;                 for (int t = 0; t < 32; ++t) bu[t] = *(const LAS unsigned*)(BH + t * BH_STRIDE + 2 * lane);
;                 LDS_FENCE();
;                 float xr = sr[gi], xi = si[gi];
; #pragma unroll
;                 for (int t = 0; t < 32; ++t) {
;                     if (sample && t == 0) { xr = s0ar; xi = s0ai; }
;     ...
;                     for (int r = 0; r < 4; ++r) {
;                         LAS bf16* up = XU + (16 * rb + 4 * kq + r) * XU_STRIDE + 16 * gi + fr;
;                         const float u = __uint_as_float((unsigned)(*up) << 16);
;                         *up = f2bf(gelu_t(acc[r] + dsk[gi] * u));
;                     }
	v_lshlrev_b32_e32 v8, 16, v8
	v_lshlrev_b32_e32 v9, 16, v9
	v_lshlrev_b32_e32 v10, 16, v10
	v_lshlrev_b32_e32 v11, 16, v11
	v_lshlrev_b32_e32 v12, 16, v12
	v_lshlrev_b32_e32 v13, 16, v13
	v_lshlrev_b32_e32 v14, 16, v14
	v_lshlrev_b32_e32 v15, 16, v15
	v_mov_b32_e32 v206, 0x3d372713
	v_mov_b32_e32 v208, 0x3fcc422a
	v_mov_b32_e32 v210, 0xbfb8aa3b
	v_mov_b32_e32 v212, 1.0
	v_mov_b32_e32 v230, v175
	v_pk_fma_f32 v[0:1], v[230:231], v[8:9], v[0:1] op_sel_hi:[0,1,1]
	v_pk_fma_f32 v[2:3], v[230:231], v[10:11], v[2:3] op_sel_hi:[0,1,1]
	v_pk_fma_f32 v[4:5], v[230:231], v[12:13], v[4:5] op_sel_hi:[0,1,1]
	v_pk_fma_f32 v[6:7], v[230:231], v[14:15], v[6:7] op_sel_hi:[0,1,1]
	v_pk_mul_f32 v[198:199], v[0:1], v[206:207] op_sel_hi:[1,0]
	v_pk_mul_f32 v[200:201], v[2:3], v[206:207] op_sel_hi:[1,0]
	v_pk_mul_f32 v[202:203], v[4:5], v[206:207] op_sel_hi:[1,0]
	v_pk_mul_f32 v[204:205], v[6:7], v[206:207] op_sel_hi:[1,0]
	v_pk_mul_f32 v[198:199], v[0:1], v[198:199]
	v_pk_mul_f32 v[200:201], v[2:3], v[200:201]
	v_pk_mul_f32 v[202:203], v[4:5], v[202:203]
	v_pk_mul_f32 v[204:205], v[6:7], v[204:205]
	v_pk_fma_f32 v[198:199], v[0:1], v[198:199], v[0:1]
	v_pk_fma_f32 v[200:201], v[2:3], v[200:201], v[2:3]
	v_pk_fma_f32 v[202:203], v[4:5], v[202:203], v[4:5]
	v_pk_fma_f32 v[204:205], v[6:7], v[204:205], v[6:7]
	v_pk_mul_f32 v[198:199], v[198:199], v[208:209] op_sel_hi:[1,0]
	v_pk_mul_f32 v[200:201], v[200:201], v[208:209] op_sel_hi:[1,0]
	v_pk_mul_f32 v[202:203], v[202:203], v[208:209] op_sel_hi:[1,0]
	v_pk_mul_f32 v[204:205], v[204:205], v[208:209] op_sel_hi:[1,0]
	v_pk_mul_f32 v[198:199], v[198:199], v[210:211] op_sel_hi:[1,0]
	v_pk_mul_f32 v[200:201], v[200:201], v[210:211] op_sel_hi:[1,0]
	v_pk_mul_f32 v[202:203], v[202:203], v[210:211] op_sel_hi:[1,0]
	v_pk_mul_f32 v[204:205], v[204:205], v[210:211] op_sel_hi:[1,0]
	v_exp_f32_e32 v198, v198
	v_exp_f32_e32 v199, v199
	v_exp_f32_e32 v200, v200
	v_exp_f32_e32 v201, v201
	v_exp_f32_e32 v202, v202
	v_exp_f32_e32 v203, v203
	v_exp_f32_e32 v204, v204
	v_exp_f32_e32 v205, v205
	v_pk_add_f32 v[198:199], v[198:199], v[212:213] op_sel_hi:[1,0]
	v_pk_add_f32 v[200:201], v[200:201], v[212:213] op_sel_hi:[1,0]
	v_pk_add_f32 v[202:203], v[202:203], v[212:213] op_sel_hi:[1,0]
	v_pk_add_f32 v[204:205], v[204:205], v[212:213] op_sel_hi:[1,0]
	v_rcp_f32_e32 v198, v198
	v_rcp_f32_e32 v199, v199
	v_rcp_f32_e32 v200, v200
	v_rcp_f32_e32 v201, v201
	v_rcp_f32_e32 v202, v202
	v_rcp_f32_e32 v203, v203
	v_rcp_f32_e32 v204, v204
	v_rcp_f32_e32 v205, v205
	v_pk_mul_f32 v[0:1], v[0:1], v[198:199]
	v_pk_mul_f32 v[2:3], v[2:3], v[200:201]
	v_pk_mul_f32 v[4:5], v[4:5], v[202:203]
	v_pk_mul_f32 v[6:7], v[6:7], v[204:205]
	v_cvt_pk_bf16_f32 v0, v0, v101
	v_cvt_pk_bf16_f32 v1, v1, v101
	v_cvt_pk_bf16_f32 v2, v2, v101
	v_cvt_pk_bf16_f32 v3, v3, v101
	v_cvt_pk_bf16_f32 v4, v4, v101
	v_cvt_pk_bf16_f32 v5, v5, v101
	v_cvt_pk_bf16_f32 v6, v6, v101
	v_cvt_pk_bf16_f32 v7, v7, v101
	ds_write_b16 v195, v0
	ds_write_b16 v195, v1 offset:144
	ds_write_b16 v195, v2 offset:288
	ds_write_b16 v195, v3 offset:432
	ds_write_b16 v195, v4 offset:2304
	ds_write_b16 v195, v5 offset:2448
	ds_write_b16 v195, v6 offset:2592
	ds_write_b16 v195, v7 offset:2736
	s_waitcnt lgkmcnt(0)
	global_load_dwordx4 v[76:79], v[136:137], off
	global_load_dwordx4 v[72:75], v[138:139], off
	global_load_dwordx4 v[68:71], v[140:141], off
	global_load_dwordx4 v[64:67], v[142:143], off
	ds_read_b128 v[250:253], v192 offset:32
	s_waitcnt vmcnt(11) lgkmcnt(0)
	v_mfma_f32_32x32x16_bf16 v[0:15], v[250:253], v[92:95], 0
	global_load_dwordx4 v[44:47], v[144:145], off
	global_load_dwordx4 v[40:43], v[144:145], off offset:1024
	global_load_dwordx4 v[32:35], v[144:145], off offset:2048
	global_load_dwordx4 v[36:39], v[144:145], off offset:3072
	s_waitcnt vmcnt(14)
	v_mfma_f32_32x32x16_bf16 v[214:229], v[250:253], v[88:91], 0
	s_waitcnt vmcnt(13)
	v_mfma_f32_32x32x16_bf16 v[234:249], v[250:253], v[84:87], 0
	s_waitcnt vmcnt(12)
	v_mfma_f32_32x32x16_bf16 v[198:213], v[250:253], v[80:83], 0
	s_nop 11
	v_permlane32_swap_b32_e32 v0, v234
	v_permlane32_swap_b32_e32 v1, v235
	v_permlane32_swap_b32_e32 v2, v236
	v_permlane32_swap_b32_e32 v3, v237
	v_permlane32_swap_b32_e32 v4, v238
	v_permlane32_swap_b32_e32 v5, v239
	v_permlane32_swap_b32_e32 v6, v240
	v_permlane32_swap_b32_e32 v7, v241
	v_permlane32_swap_b32_e32 v8, v242
	v_permlane32_swap_b32_e32 v9, v243
	v_permlane32_swap_b32_e32 v10, v244
	v_permlane32_swap_b32_e32 v11, v245
	v_permlane32_swap_b32_e32 v12, v246
	v_permlane32_swap_b32_e32 v13, v247
	v_permlane32_swap_b32_e32 v14, v248
	v_permlane32_swap_b32_e32 v15, v249
	v_permlane32_swap_b32_e32 v214, v198
	v_permlane32_swap_b32_e32 v215, v199
	v_permlane32_swap_b32_e32 v216, v200
	v_permlane32_swap_b32_e32 v217, v201
	v_permlane32_swap_b32_e32 v218, v202
	v_permlane32_swap_b32_e32 v219, v203
	v_permlane32_swap_b32_e32 v220, v204
	v_permlane32_swap_b32_e32 v221, v205
	v_permlane32_swap_b32_e32 v222, v206
	v_permlane32_swap_b32_e32 v223, v207
	v_permlane32_swap_b32_e32 v224, v208
	v_permlane32_swap_b32_e32 v225, v209
	v_permlane32_swap_b32_e32 v226, v210
	v_permlane32_swap_b32_e32 v227, v211
	v_permlane32_swap_b32_e32 v228, v212
	v_permlane32_swap_b32_e32 v229, v213
	v_fma_f32 v0, -v177, v113, v0
	v_fma_f32 v214, v177, v115, v214
	v_fma_f32 v115, v176, v115, v0
	v_fma_f32 v113, v176, v113, v214
	v_cvt_pk_bf16_f32 v197, v115, v113
	ds_write_b32 v107, v197 offset:4608
	v_fma_f32 v1, -v177, v113, v1
	v_fma_f32 v215, v177, v115, v215
	v_fma_f32 v115, v176, v115, v1
	v_fma_f32 v113, v176, v113, v215
	v_cvt_pk_bf16_f32 v197, v115, v113
	ds_write_b32 v107, v197 offset:4880
	v_fma_f32 v2, -v177, v113, v2
; __device__ __forceinline__ float bf_lo(unsigned w) { return __uint_as_float(w << 16); }
; __device__ __forceinline__ float bf_hi(unsigned w) { return __uint_as_float(w & 0xffff0000u); }
; #define LAS __attribute__((address_space(3)))
; __device__ __forceinline__ unsigned cvt_pk_nv(float lo, float hi) { unsigned r; asm("v_cvt_pk_bf16_f32 %0, %1, %2" : "=v"(r) : "v"(lo), "v"(hi)); return r; }
;     __device__ __forceinline__ float* out() const { return (float*)karg_in(33); }
; template <bool PASS2>
; __device__ __forceinline__ void s5_tile(const Ctx& C, int T, int sb_lo, int sb_hi, LAS unsigned char* lds, int wave, int lane) {
;     ...
;                 float xr = sr[gi], xi = si[gi];
; #pragma unroll
;                 for (int t = 0; t < 32; ++t) {
;                     if (sample && t == 0) { xr = s0ar; xi = s0ai; }
;                     if (sample && t == 16) { xr = s0br; xi = s0bi; }
;                     const float nr = fmaf(lr[gi], xr, fmaf(-li[gi], xi, bf_lo(bu[t]))), ni = fmaf(lr[gi], xi, fmaf(li[gi], xr, bf_hi(bu[t])));
;                     xr = nr; xi = ni;
;                     if (PASS2) {
;                         *(LAS unsigned*)(BH + t * BH_STRIDE + 2 * lane) = cvt_pk_nv(xr, xi);
;                         if (sample && (t & 15) == 15) { const int seq = 2 * sb + (t >> 4);
;                             C.out()[OFF_SRE_S + ((size_t)seq * NG + g) * NP + lane] = xr; C.out()[OFF_SIM_S + ((size_t)seq * NG + g) * NP + lane] = xi; }
;                     }
;                 }
	v_fma_f32 v216, v177, v115, v216
	v_fma_f32 v115, v176, v115, v2
	v_fma_f32 v113, v176, v113, v216
	v_cvt_pk_bf16_f32 v197, v115, v113
	ds_write_b32 v107, v197 offset:5152
	v_fma_f32 v3, -v177, v113, v3
	v_fma_f32 v217, v177, v115, v217
	v_fma_f32 v115, v176, v115, v3
	v_fma_f32 v113, v176, v113, v217
	v_cvt_pk_bf16_f32 v197, v115, v113
	ds_write_b32 v107, v197 offset:5424
	v_fma_f32 v234, -v177, v113, v234
	v_fma_f32 v198, v177, v115, v198
	v_fma_f32 v115, v176, v115, v234
	v_fma_f32 v113, v176, v113, v198
	v_cvt_pk_bf16_f32 v197, v115, v113
	ds_write_b32 v107, v197 offset:5696
	v_fma_f32 v235, -v177, v113, v235
	v_fma_f32 v199, v177, v115, v199
	v_fma_f32 v115, v176, v115, v235
	v_fma_f32 v113, v176, v113, v199
	v_cvt_pk_bf16_f32 v197, v115, v113
	ds_write_b32 v107, v197 offset:5968
	v_fma_f32 v236, -v177, v113, v236
	v_fma_f32 v200, v177, v115, v200
	v_fma_f32 v115, v176, v115, v236
	v_fma_f32 v113, v176, v113, v200
	v_cvt_pk_bf16_f32 v197, v115, v113
	ds_write_b32 v107, v197 offset:6240
	v_fma_f32 v237, -v177, v113, v237
	v_fma_f32 v201, v177, v115, v201
	v_fma_f32 v115, v176, v115, v237
	v_fma_f32 v113, v176, v113, v201
	v_cvt_pk_bf16_f32 v197, v115, v113
	ds_write_b32 v107, v197 offset:6512
	v_fma_f32 v4, -v177, v113, v4
	v_fma_f32 v218, v177, v115, v218
	v_fma_f32 v115, v176, v115, v4
	v_fma_f32 v113, v176, v113, v218
	v_cvt_pk_bf16_f32 v197, v115, v113
	ds_write_b32 v107, v197 offset:6784
	v_fma_f32 v5, -v177, v113, v5
	v_fma_f32 v219, v177, v115, v219
	v_fma_f32 v115, v176, v115, v5
	v_fma_f32 v113, v176, v113, v219
	v_cvt_pk_bf16_f32 v197, v115, v113
	ds_write_b32 v107, v197 offset:7056
	v_fma_f32 v6, -v177, v113, v6
	v_fma_f32 v220, v177, v115, v220
	v_fma_f32 v115, v176, v115, v6
	v_fma_f32 v113, v176, v113, v220
	v_cvt_pk_bf16_f32 v197, v115, v113
	ds_write_b32 v107, v197 offset:7328
	v_fma_f32 v7, -v177, v113, v7
	v_fma_f32 v221, v177, v115, v221
	v_fma_f32 v115, v176, v115, v7
	v_fma_f32 v113, v176, v113, v221
	v_cvt_pk_bf16_f32 v197, v115, v113
	ds_write_b32 v107, v197 offset:7600
	v_fma_f32 v238, -v177, v113, v238
	v_fma_f32 v202, v177, v115, v202
	v_fma_f32 v115, v176, v115, v238
	v_fma_f32 v113, v176, v113, v202
	v_cvt_pk_bf16_f32 v197, v115, v113
	ds_write_b32 v107, v197 offset:7872
	v_fma_f32 v239, -v177, v113, v239
	v_fma_f32 v203, v177, v115, v203
	v_fma_f32 v115, v176, v115, v239
	v_fma_f32 v113, v176, v113, v203
	v_cvt_pk_bf16_f32 v197, v115, v113
	ds_write_b32 v107, v197 offset:8144
	v_fma_f32 v240, -v177, v113, v240
	v_fma_f32 v204, v177, v115, v204
	v_fma_f32 v115, v176, v115, v240
	v_fma_f32 v113, v176, v113, v204
	v_cvt_pk_bf16_f32 v197, v115, v113
	ds_write_b32 v107, v197 offset:8416
	v_fma_f32 v241, -v177, v113, v241
	v_fma_f32 v205, v177, v115, v205
	v_fma_f32 v115, v176, v115, v241
	v_fma_f32 v113, v176, v113, v205
	v_cvt_pk_bf16_f32 v197, v115, v113
	ds_write_b32 v107, v197 offset:8688
	v_fma_f32 v8, -v177, v113, v8
	v_fma_f32 v222, v177, v115, v222
	v_fma_f32 v115, v176, v115, v8
	v_fma_f32 v113, v176, v113, v222
	v_cvt_pk_bf16_f32 v197, v115, v113
	ds_write_b32 v107, v197 offset:8960
	v_fma_f32 v9, -v177, v113, v9
	v_fma_f32 v223, v177, v115, v223
	v_fma_f32 v115, v176, v115, v9
	v_fma_f32 v113, v176, v113, v223
	v_cvt_pk_bf16_f32 v197, v115, v113
	ds_write_b32 v107, v197 offset:9232
	v_fma_f32 v10, -v177, v113, v10
	v_fma_f32 v224, v177, v115, v224
	v_fma_f32 v115, v176, v115, v10
	v_fma_f32 v113, v176, v113, v224
	v_cvt_pk_bf16_f32 v197, v115, v113
	ds_write_b32 v107, v197 offset:9504
	v_fma_f32 v11, -v177, v113, v11
	v_fma_f32 v225, v177, v115, v225
	v_fma_f32 v115, v176, v115, v11
	v_fma_f32 v113, v176, v113, v225
	v_cvt_pk_bf16_f32 v197, v115, v113
	ds_write_b32 v107, v197 offset:9776
	v_fma_f32 v242, -v177, v113, v242
	v_fma_f32 v206, v177, v115, v206
	v_fma_f32 v115, v176, v115, v242
	v_fma_f32 v113, v176, v113, v206
	v_cvt_pk_bf16_f32 v197, v115, v113
	ds_write_b32 v107, v197 offset:10048
	v_fma_f32 v243, -v177, v113, v243
	v_fma_f32 v207, v177, v115, v207
	v_fma_f32 v115, v176, v115, v243
	v_fma_f32 v113, v176, v113, v207
	v_cvt_pk_bf16_f32 v197, v115, v113
	ds_write_b32 v107, v197 offset:10320
	v_fma_f32 v244, -v177, v113, v244
	v_fma_f32 v208, v177, v115, v208
	v_fma_f32 v115, v176, v115, v244
	v_fma_f32 v113, v176, v113, v208
	v_cvt_pk_bf16_f32 v197, v115, v113
	ds_write_b32 v107, v197 offset:10592
	v_fma_f32 v245, -v177, v113, v245
	v_fma_f32 v209, v177, v115, v209
	v_fma_f32 v115, v176, v115, v245
	v_fma_f32 v113, v176, v113, v209
	v_cvt_pk_bf16_f32 v197, v115, v113
	ds_write_b32 v107, v197 offset:10864
	v_fma_f32 v12, -v177, v113, v12
	v_fma_f32 v226, v177, v115, v226
	v_fma_f32 v115, v176, v115, v12
	v_fma_f32 v113, v176, v113, v226
	v_cvt_pk_bf16_f32 v197, v115, v113
	ds_write_b32 v107, v197 offset:11136
	v_fma_f32 v13, -v177, v113, v13
	v_fma_f32 v227, v177, v115, v227
	v_fma_f32 v115, v176, v115, v13
	v_fma_f32 v113, v176, v113, v227
	v_cvt_pk_bf16_f32 v197, v115, v113
	ds_write_b32 v107, v197 offset:11408
	v_fma_f32 v14, -v177, v113, v14
	v_fma_f32 v228, v177, v115, v228
	v_fma_f32 v115, v176, v115, v14
	v_fma_f32 v113, v176, v113, v228
	v_cvt_pk_bf16_f32 v197, v115, v113
	ds_write_b32 v107, v197 offset:11680
	v_fma_f32 v15, -v177, v113, v15
	v_fma_f32 v229, v177, v115, v229
	v_fma_f32 v115, v176, v115, v15
	v_fma_f32 v113, v176, v113, v229
	v_cvt_pk_bf16_f32 v197, v115, v113
	ds_write_b32 v107, v197 offset:11952
	v_fma_f32 v246, -v177, v113, v246
	v_fma_f32 v210, v177, v115, v210
	v_fma_f32 v115, v176, v115, v246
	v_fma_f32 v113, v176, v113, v210
	v_cvt_pk_bf16_f32 v197, v115, v113
	ds_write_b32 v107, v197 offset:12224
	v_fma_f32 v247, -v177, v113, v247
	v_fma_f32 v211, v177, v115, v211
	v_fma_f32 v115, v176, v115, v247
	v_fma_f32 v113, v176, v113, v211
	v_cvt_pk_bf16_f32 v197, v115, v113
	ds_write_b32 v107, v197 offset:12496
	v_fma_f32 v248, -v177, v113, v248
	v_fma_f32 v212, v177, v115, v212
	v_fma_f32 v115, v176, v115, v248
	v_fma_f32 v113, v176, v113, v212
	v_cvt_pk_bf16_f32 v197, v115, v113
	ds_write_b32 v107, v197 offset:12768
	v_fma_f32 v249, -v177, v113, v249
	v_fma_f32 v213, v177, v115, v213
	v_fma_f32 v115, v176, v115, v249
	v_fma_f32 v113, v176, v113, v213
	v_cvt_pk_bf16_f32 v197, v115, v113
	ds_write_b32 v107, v197 offset:13040
	s_waitcnt lgkmcnt(0)
; __device__ __forceinline__ float gelu_t(float x) { const float u = 1.5957691216057308f * (x + 0.044715f * x * x * x); return x * sigmoid_f(u); }
; #define LAS __attribute__((address_space(3)))
; __device__ __forceinline__ bf16 f2bf(float f) { return (bf16)(cvt_pk_nv(f, 0.f) & 0xffffu); }
; template <bool PASS2>
; __device__ __forceinline__ void s5_tile(const Ctx& C, int T, int sb_lo, int sb_hi, LAS unsigned char* lds, int wave, int lane) {
;     ...
;             if (PASS2) {
; #pragma unroll
;                 for (int rb = 0; rb < 2; ++rb) {
;                     v4f acc = (v4f){0.f, 0.f, 0.f, 0.f};
; #pragma unroll
;                     for (int ks = 0; ks < 4; ++ks) {
;                         const bfx8 sa = *(const LAS bfx8*)(BH + (16 * rb + fr) * BH_STRIDE + 32 * ks + 8 * kq);
;                         acc = __builtin_amdgcn_mfma_f32_16x16x32_bf16(sa, cm[ks], acc, 0, 0, 0);
;                     }
; #pragma unroll
;                     for (int r = 0; r < 4; ++r) {
;                         LAS bf16* up = XU + (16 * rb + 4 * kq + r) * XU_STRIDE + 16 * gi + fr;
;                         const float u = __uint_as_float((unsigned)(*up) << 16);
;                         *up = f2bf(gelu_t(acc[r] + dsk[gi] * u));
;                     }
;                 }
	ds_read_b128 v[214:217], v194 offset:4608
	ds_read_b128 v[218:221], v194 offset:4672
	ds_read_b128 v[222:225], v194 offset:4736
	ds_read_b128 v[226:229], v194 offset:4800
	ds_read_b128 v[234:237], v194 offset:8960
	ds_read_b128 v[238:241], v194 offset:9024
	ds_read_b128 v[242:245], v194 offset:9088
	ds_read_b128 v[246:249], v194 offset:9152
	ds_read_u16 v8, v195 offset:32
	ds_read_u16 v9, v195 offset:176
	ds_read_u16 v10, v195 offset:320
	ds_read_u16 v11, v195 offset:464
	ds_read_u16 v12, v195 offset:2336
	ds_read_u16 v13, v195 offset:2480
	ds_read_u16 v14, v195 offset:2624
	ds_read_u16 v15, v195 offset:2768
	s_waitcnt vmcnt(8) lgkmcnt(8)
	v_mfma_f32_16x16x32_bf16 v[0:3], v[214:217], v[60:63], 0
	v_mfma_f32_16x16x32_bf16 v[4:7], v[234:237], v[60:63], 0
	v_mfma_f32_16x16x32_bf16 v[0:3], v[218:221], v[56:59], v[0:3]
	v_mfma_f32_16x16x32_bf16 v[4:7], v[238:241], v[56:59], v[4:7]
	v_mfma_f32_16x16x32_bf16 v[0:3], v[222:225], v[48:51], v[0:3]
	v_mfma_f32_16x16x32_bf16 v[4:7], v[242:245], v[48:51], v[4:7]
	v_mfma_f32_16x16x32_bf16 v[0:3], v[226:229], v[52:55], v[0:3]
	v_mfma_f32_16x16x32_bf16 v[4:7], v[246:249], v[52:55], v[4:7]
	s_waitcnt lgkmcnt(0)
	v_lshlrev_b32_e32 v8, 16, v8
	v_lshlrev_b32_e32 v9, 16, v9
	v_lshlrev_b32_e32 v10, 16, v10
	v_lshlrev_b32_e32 v11, 16, v11
	v_lshlrev_b32_e32 v12, 16, v12
	v_lshlrev_b32_e32 v13, 16, v13
	v_lshlrev_b32_e32 v14, 16, v14
	v_lshlrev_b32_e32 v15, 16, v15
	v_mov_b32_e32 v206, 0x3d372713
	v_mov_b32_e32 v208, 0x3fcc422a
	v_mov_b32_e32 v210, 0xbfb8aa3b
	v_mov_b32_e32 v212, 1.0
	v_mov_b32_e32 v230, v178
	v_pk_fma_f32 v[0:1], v[230:231], v[8:9], v[0:1] op_sel_hi:[0,1,1]
	v_pk_fma_f32 v[2:3], v[230:231], v[10:11], v[2:3] op_sel_hi:[0,1,1]
	v_pk_fma_f32 v[4:5], v[230:231], v[12:13], v[4:5] op_sel_hi:[0,1,1]
	v_pk_fma_f32 v[6:7], v[230:231], v[14:15], v[6:7] op_sel_hi:[0,1,1]
	v_pk_mul_f32 v[198:199], v[0:1], v[206:207] op_sel_hi:[1,0]
	v_pk_mul_f32 v[200:201], v[2:3], v[206:207] op_sel_hi:[1,0]
	v_pk_mul_f32 v[202:203], v[4:5], v[206:207] op_sel_hi:[1,0]
	v_pk_mul_f32 v[204:205], v[6:7], v[206:207] op_sel_hi:[1,0]
	v_pk_mul_f32 v[198:199], v[0:1], v[198:199]
	v_pk_mul_f32 v[200:201], v[2:3], v[200:201]
	v_pk_mul_f32 v[202:203], v[4:5], v[202:203]
	v_pk_mul_f32 v[204:205], v[6:7], v[204:205]
	v_pk_fma_f32 v[198:199], v[0:1], v[198:199], v[0:1]
	v_pk_fma_f32 v[200:201], v[2:3], v[200:201], v[2:3]
	v_pk_fma_f32 v[202:203], v[4:5], v[202:203], v[4:5]
	v_pk_fma_f32 v[204:205], v[6:7], v[204:205], v[6:7]
	v_pk_mul_f32 v[198:199], v[198:199], v[208:209] op_sel_hi:[1,0]
	v_pk_mul_f32 v[200:201], v[200:201], v[208:209] op_sel_hi:[1,0]
	v_pk_mul_f32 v[202:203], v[202:203], v[208:209] op_sel_hi:[1,0]
	v_pk_mul_f32 v[204:205], v[204:205], v[208:209] op_sel_hi:[1,0]
	v_pk_mul_f32 v[198:199], v[198:199], v[210:211] op_sel_hi:[1,0]
	v_pk_mul_f32 v[200:201], v[200:201], v[210:211] op_sel_hi:[1,0]
	v_pk_mul_f32 v[202:203], v[202:203], v[210:211] op_sel_hi:[1,0]
	v_pk_mul_f32 v[204:205], v[204:205], v[210:211] op_sel_hi:[1,0]
	v_exp_f32_e32 v198, v198
	v_exp_f32_e32 v199, v199
	v_exp_f32_e32 v200, v200
	v_exp_f32_e32 v201, v201
	v_exp_f32_e32 v202, v202
	v_exp_f32_e32 v203, v203
	v_exp_f32_e32 v204, v204
	v_exp_f32_e32 v205, v205
	v_pk_add_f32 v[198:199], v[198:199], v[212:213] op_sel_hi:[1,0]
	v_pk_add_f32 v[200:201], v[200:201], v[212:213] op_sel_hi:[1,0]
	v_pk_add_f32 v[202:203], v[202:203], v[212:213] op_sel_hi:[1,0]
	v_pk_add_f32 v[204:205], v[204:205], v[212:213] op_sel_hi:[1,0]
	v_rcp_f32_e32 v198, v198
	v_rcp_f32_e32 v199, v199
	v_rcp_f32_e32 v200, v200
	v_rcp_f32_e32 v201, v201
	v_rcp_f32_e32 v202, v202
	v_rcp_f32_e32 v203, v203
	v_rcp_f32_e32 v204, v204
	v_rcp_f32_e32 v205, v205
	v_pk_mul_f32 v[0:1], v[0:1], v[198:199]
	v_pk_mul_f32 v[2:3], v[2:3], v[200:201]
	v_pk_mul_f32 v[4:5], v[4:5], v[202:203]
	v_pk_mul_f32 v[6:7], v[6:7], v[204:205]
	v_cvt_pk_bf16_f32 v0, v0, v101
	v_cvt_pk_bf16_f32 v1, v1, v101
	v_cvt_pk_bf16_f32 v2, v2, v101
	v_cvt_pk_bf16_f32 v3, v3, v101
	v_cvt_pk_bf16_f32 v4, v4, v101
	v_cvt_pk_bf16_f32 v5, v5, v101
	v_cvt_pk_bf16_f32 v6, v6, v101
	v_cvt_pk_bf16_f32 v7, v7, v101
	ds_write_b16 v195, v0 offset:32
	ds_write_b16 v195, v1 offset:176
	ds_write_b16 v195, v2 offset:320
	ds_write_b16 v195, v3 offset:464
	ds_write_b16 v195, v4 offset:2336
	ds_write_b16 v195, v5 offset:2480
	ds_write_b16 v195, v6 offset:2624
	ds_write_b16 v195, v7 offset:2768
	s_waitcnt lgkmcnt(0)
	global_load_dwordx4 v[92:95], v[146:147], off
	global_load_dwordx4 v[88:91], v[148:149], off
	global_load_dwordx4 v[84:87], v[150:151], off
	global_load_dwordx4 v[80:83], v[152:153], off
	ds_read_b128 v[250:253], v192 offset:64
	s_waitcnt vmcnt(11) lgkmcnt(0)
	v_mfma_f32_32x32x16_bf16 v[0:15], v[250:253], v[76:79], 0
	global_load_dwordx4 v[60:63], v[154:155], off
	global_load_dwordx4 v[56:59], v[154:155], off offset:1024
	global_load_dwordx4 v[48:51], v[154:155], off offset:2048
	global_load_dwordx4 v[52:55], v[154:155], off offset:3072
	s_waitcnt vmcnt(14)
	v_mfma_f32_32x32x16_bf16 v[214:229], v[250:253], v[72:75], 0
	s_waitcnt vmcnt(13)
	v_mfma_f32_32x32x16_bf16 v[234:249], v[250:253], v[68:71], 0
	s_waitcnt vmcnt(12)
; __device__ __forceinline__ float bf_lo(unsigned w) { return __uint_as_float(w << 16); }
; __device__ __forceinline__ float bf_hi(unsigned w) { return __uint_as_float(w & 0xffff0000u); }
; #define LAS __attribute__((address_space(3)))
; #define LDS_FENCE() asm volatile("s_waitcnt lgkmcnt(0)" ::: "memory")
; __device__ __forceinline__ unsigned cvt_pk_c(float lo, float hi) { const v2f v = {lo, hi}; const bf16x2_t b = __builtin_convertvector(v, bf16x2_t); return __builtin_bit_cast(unsigned, b); }
; template <bool PASS2>
; __device__ __forceinline__ void s5_tile(const Ctx& C, int T, int sb_lo, int sb_hi, LAS unsigned char* lds, int wave, int lane) {
;     ...
;             const bfx8 a = *(const LAS bfx8*)(XU + tl * XU_STRIDE + 16 * gi + 8 * hh);
; #pragma unroll
;             for (int cb = 0; cb < 4; ++cb) {
;                 v16f acc;
; #pragma unroll
;                 for (int r = 0; r < 16; ++r) acc[r] = 0.f;
;                 acc = __builtin_amdgcn_mfma_f32_32x32x16_bf16(bb[cb], a, acc, 0, 0, 0);
; #pragma unroll
;                 for (int rg = 0; rg < 4; ++rg) { v2u w; w.x = cvt_pk_c(acc[4 * rg], acc[4 * rg + 1]); w.y = cvt_pk_c(acc[4 * rg + 2], acc[4 * rg + 3]);
;                     *(LAS v2u*)(BH + tl * BH_STRIDE + cb * 32 + 8 * rg + 4 * hh) = w; }
;             }
;             LDS_FENCE();
;             {
;                 unsigned bu[32];
; #pragma unroll
;                 for (int t = 0; t < 32; ++t) bu[t] = *(const LAS unsigned*)(BH + t * BH_STRIDE + 2 * lane);
;                 LDS_FENCE();
;                 float xr = sr[gi], xi = si[gi];
; #pragma unroll
;                 for (int t = 0; t < 32; ++t) {
;                     if (sample && t == 0) { xr = s0ar; xi = s0ai; }
;                     if (sample && t == 16) { xr = s0br; xi = s0bi; }
;                     const float nr = fmaf(lr[gi], xr, fmaf(-li[gi], xi, bf_lo(bu[t]))), ni = fmaf(lr[gi], xi, fmaf(li[gi], xr, bf_hi(bu[t])));
;                     xr = nr; xi = ni;
;                     if (PASS2) {
;                         *(LAS unsigned*)(BH + t * BH_STRIDE + 2 * lane) = cvt_pk_nv(xr, xi);
;                         if (sample && (t & 15) == 15) { const int seq = 2 * sb + (t >> 4);
;                             C.out()[OFF_SRE_S + ((size_t)seq * NG + g) * NP + lane] = xr; C.out()[OFF_SIM_S + ((size_t)seq * NG + g) * NP + lane] = xi; }
;                     }
;                 }
	v_mfma_f32_32x32x16_bf16 v[198:213], v[250:253], v[64:67], 0
	s_nop 11
	v_permlane32_swap_b32_e32 v0, v234
	v_permlane32_swap_b32_e32 v1, v235
	v_permlane32_swap_b32_e32 v2, v236
	v_permlane32_swap_b32_e32 v3, v237
	v_permlane32_swap_b32_e32 v4, v238
	v_permlane32_swap_b32_e32 v5, v239
	v_permlane32_swap_b32_e32 v6, v240
	v_permlane32_swap_b32_e32 v7, v241
	v_permlane32_swap_b32_e32 v8, v242
	v_permlane32_swap_b32_e32 v9, v243
	v_permlane32_swap_b32_e32 v10, v244
	v_permlane32_swap_b32_e32 v11, v245
	v_permlane32_swap_b32_e32 v12, v246
	v_permlane32_swap_b32_e32 v13, v247
	v_permlane32_swap_b32_e32 v14, v248
	v_permlane32_swap_b32_e32 v15, v249
	v_permlane32_swap_b32_e32 v214, v198
	v_permlane32_swap_b32_e32 v215, v199
	v_permlane32_swap_b32_e32 v216, v200
	v_permlane32_swap_b32_e32 v217, v201
	v_permlane32_swap_b32_e32 v218, v202
	v_permlane32_swap_b32_e32 v219, v203
	v_permlane32_swap_b32_e32 v220, v204
	v_permlane32_swap_b32_e32 v221, v205
	v_permlane32_swap_b32_e32 v222, v206
	v_permlane32_swap_b32_e32 v223, v207
	v_permlane32_swap_b32_e32 v224, v208
	v_permlane32_swap_b32_e32 v225, v209
	v_permlane32_swap_b32_e32 v226, v210
	v_permlane32_swap_b32_e32 v227, v211
	v_permlane32_swap_b32_e32 v228, v212
	v_permlane32_swap_b32_e32 v229, v213
	v_fma_f32 v0, -v180, v108, v0
	v_fma_f32 v214, v180, v110, v214
	v_fma_f32 v110, v179, v110, v0
	v_fma_f32 v108, v179, v108, v214
	v_cvt_pk_bf16_f32 v197, v110, v108
	ds_write_b32 v107, v197 offset:4608
	v_fma_f32 v1, -v180, v108, v1
	v_fma_f32 v215, v180, v110, v215
	v_fma_f32 v110, v179, v110, v1
	v_fma_f32 v108, v179, v108, v215
	v_cvt_pk_bf16_f32 v197, v110, v108
	ds_write_b32 v107, v197 offset:4880
	v_fma_f32 v2, -v180, v108, v2
	v_fma_f32 v216, v180, v110, v216
	v_fma_f32 v110, v179, v110, v2
	v_fma_f32 v108, v179, v108, v216
	v_cvt_pk_bf16_f32 v197, v110, v108
	ds_write_b32 v107, v197 offset:5152
	v_fma_f32 v3, -v180, v108, v3
	v_fma_f32 v217, v180, v110, v217
	v_fma_f32 v110, v179, v110, v3
	v_fma_f32 v108, v179, v108, v217
	v_cvt_pk_bf16_f32 v197, v110, v108
	ds_write_b32 v107, v197 offset:5424
	v_fma_f32 v234, -v180, v108, v234
	v_fma_f32 v198, v180, v110, v198
	v_fma_f32 v110, v179, v110, v234
	v_fma_f32 v108, v179, v108, v198
	v_cvt_pk_bf16_f32 v197, v110, v108
	ds_write_b32 v107, v197 offset:5696
	v_fma_f32 v235, -v180, v108, v235
	v_fma_f32 v199, v180, v110, v199
	v_fma_f32 v110, v179, v110, v235
	v_fma_f32 v108, v179, v108, v199
	v_cvt_pk_bf16_f32 v197, v110, v108
	ds_write_b32 v107, v197 offset:5968
	v_fma_f32 v236, -v180, v108, v236
	v_fma_f32 v200, v180, v110, v200
	v_fma_f32 v110, v179, v110, v236
	v_fma_f32 v108, v179, v108, v200
	v_cvt_pk_bf16_f32 v197, v110, v108
	ds_write_b32 v107, v197 offset:6240
	v_fma_f32 v237, -v180, v108, v237
	v_fma_f32 v201, v180, v110, v201
	v_fma_f32 v110, v179, v110, v237
	v_fma_f32 v108, v179, v108, v201
	v_cvt_pk_bf16_f32 v197, v110, v108
	ds_write_b32 v107, v197 offset:6512
	v_fma_f32 v4, -v180, v108, v4
	v_fma_f32 v218, v180, v110, v218
	v_fma_f32 v110, v179, v110, v4
	v_fma_f32 v108, v179, v108, v218
	v_cvt_pk_bf16_f32 v197, v110, v108
	ds_write_b32 v107, v197 offset:6784
	v_fma_f32 v5, -v180, v108, v5
	v_fma_f32 v219, v180, v110, v219
	v_fma_f32 v110, v179, v110, v5
	v_fma_f32 v108, v179, v108, v219
	v_cvt_pk_bf16_f32 v197, v110, v108
	ds_write_b32 v107, v197 offset:7056
	v_fma_f32 v6, -v180, v108, v6
	v_fma_f32 v220, v180, v110, v220
	v_fma_f32 v110, v179, v110, v6
	v_fma_f32 v108, v179, v108, v220
	v_cvt_pk_bf16_f32 v197, v110, v108
	ds_write_b32 v107, v197 offset:7328
	v_fma_f32 v7, -v180, v108, v7
	v_fma_f32 v221, v180, v110, v221
	v_fma_f32 v110, v179, v110, v7
	v_fma_f32 v108, v179, v108, v221
	v_cvt_pk_bf16_f32 v197, v110, v108
	ds_write_b32 v107, v197 offset:7600
	v_fma_f32 v238, -v180, v108, v238
	v_fma_f32 v202, v180, v110, v202
	v_fma_f32 v110, v179, v110, v238
	v_fma_f32 v108, v179, v108, v202
	v_cvt_pk_bf16_f32 v197, v110, v108
	ds_write_b32 v107, v197 offset:7872
	v_fma_f32 v239, -v180, v108, v239
	v_fma_f32 v203, v180, v110, v203
	v_fma_f32 v110, v179, v110, v239
	v_fma_f32 v108, v179, v108, v203
	v_cvt_pk_bf16_f32 v197, v110, v108
	ds_write_b32 v107, v197 offset:8144
	v_fma_f32 v240, -v180, v108, v240
	v_fma_f32 v204, v180, v110, v204
	v_fma_f32 v110, v179, v110, v240
	v_fma_f32 v108, v179, v108, v204
	v_cvt_pk_bf16_f32 v197, v110, v108
	ds_write_b32 v107, v197 offset:8416
	v_fma_f32 v241, -v180, v108, v241
	v_fma_f32 v205, v180, v110, v205
	v_fma_f32 v110, v179, v110, v241
	v_fma_f32 v108, v179, v108, v205
	v_cvt_pk_bf16_f32 v197, v110, v108
	ds_write_b32 v107, v197 offset:8688
	v_fma_f32 v8, -v180, v108, v8
	v_fma_f32 v222, v180, v110, v222
	v_fma_f32 v110, v179, v110, v8
	v_fma_f32 v108, v179, v108, v222
	v_cvt_pk_bf16_f32 v197, v110, v108
	ds_write_b32 v107, v197 offset:8960
	v_fma_f32 v9, -v180, v108, v9
	v_fma_f32 v223, v180, v110, v223
	v_fma_f32 v110, v179, v110, v9
	v_fma_f32 v108, v179, v108, v223
	v_cvt_pk_bf16_f32 v197, v110, v108
	ds_write_b32 v107, v197 offset:9232
	v_fma_f32 v10, -v180, v108, v10
	v_fma_f32 v224, v180, v110, v224
	v_fma_f32 v110, v179, v110, v10
	v_fma_f32 v108, v179, v108, v224
	v_cvt_pk_bf16_f32 v197, v110, v108
	ds_write_b32 v107, v197 offset:9504
	v_fma_f32 v11, -v180, v108, v11
	v_fma_f32 v225, v180, v110, v225
	v_fma_f32 v110, v179, v110, v11
	v_fma_f32 v108, v179, v108, v225
	v_cvt_pk_bf16_f32 v197, v110, v108
	ds_write_b32 v107, v197 offset:9776
	v_fma_f32 v242, -v180, v108, v242
	v_fma_f32 v206, v180, v110, v206
	v_fma_f32 v110, v179, v110, v242
	v_fma_f32 v108, v179, v108, v206
	v_cvt_pk_bf16_f32 v197, v110, v108
	ds_write_b32 v107, v197 offset:10048
	v_fma_f32 v243, -v180, v108, v243
; __device__ __forceinline__ float bf_lo(unsigned w) { return __uint_as_float(w << 16); }
; __device__ __forceinline__ float bf_hi(unsigned w) { return __uint_as_float(w & 0xffff0000u); }
; #define LAS __attribute__((address_space(3)))
; #define LDS_FENCE() asm volatile("s_waitcnt lgkmcnt(0)" ::: "memory")
; __device__ __forceinline__ float sigmoid_f(float x) { return __builtin_amdgcn_rcpf(1.0f + __expf(-x)); }
; __device__ __forceinline__ float silu_f(float x) { return x * sigmoid_f(x); }
; template <bool PASS2>
; __device__ __forceinline__ void s5_tile(const Ctx& C, int T, int sb_lo, int sb_hi, LAS unsigned char* lds, int wave, int lane) {
;     ...
;                 for (int t = 0; t < 32; ++t) {
;                     if (sample && t == 0) { xr = s0ar; xi = s0ai; }
;                     if (sample && t == 16) { xr = s0br; xi = s0bi; }
;                     const float nr = fmaf(lr[gi], xr, fmaf(-li[gi], xi, bf_lo(bu[t]))), ni = fmaf(lr[gi], xi, fmaf(li[gi], xr, bf_hi(bu[t])));
;                     xr = nr; xi = ni;
;                     if (PASS2) {
;                         *(LAS unsigned*)(BH + t * BH_STRIDE + 2 * lane) = cvt_pk_nv(xr, xi);
;                         if (sample && (t & 15) == 15) { const int seq = 2 * sb + (t >> 4);
;                             C.out()[OFF_SRE_S + ((size_t)seq * NG + g) * NP + lane] = xr; C.out()[OFF_SIM_S + ((size_t)seq * NG + g) * NP + lane] = xi; }
;                     }
;                 }
;                 sr[gi] = xr; si[gi] = xi;
;             }
;             LDS_FENCE();
;             if (PASS2) {
; #pragma unroll
;                 for (int rb = 0; rb < 2; ++rb) {
;                     v4f acc = (v4f){0.f, 0.f, 0.f, 0.f};
; #pragma unroll
;                     for (int ks = 0; ks < 4; ++ks) {
;                         const bfx8 sa = *(const LAS bfx8*)(BH + (16 * rb + fr) * BH_STRIDE + 32 * ks + 8 * kq);
;                         acc = __builtin_amdgcn_mfma_f32_16x16x32_bf16(sa, cm[ks], acc, 0, 0, 0);
;                     }
; #pragma unroll
;                     for (int r = 0; r < 4; ++r) {
;                         LAS bf16* up = XU + (16 * rb + 4 * kq + r) * XU_STRIDE + 16 * gi + fr;
;                         const float u = __uint_as_float((unsigned)(*up) << 16);
;                         *up = f2bf(gelu_t(acc[r] + dsk[gi] * u));
;                     }
;                 }
;                 LDS_FENCE();
	v_fma_f32 v207, v180, v110, v207
	v_fma_f32 v110, v179, v110, v243
	v_fma_f32 v108, v179, v108, v207
	v_cvt_pk_bf16_f32 v197, v110, v108
	ds_write_b32 v107, v197 offset:10320
	v_fma_f32 v244, -v180, v108, v244
	v_fma_f32 v208, v180, v110, v208
	v_fma_f32 v110, v179, v110, v244
	v_fma_f32 v108, v179, v108, v208
	v_cvt_pk_bf16_f32 v197, v110, v108
	ds_write_b32 v107, v197 offset:10592
	v_fma_f32 v245, -v180, v108, v245
	v_fma_f32 v209, v180, v110, v209
	v_fma_f32 v110, v179, v110, v245
	v_fma_f32 v108, v179, v108, v209
	v_cvt_pk_bf16_f32 v197, v110, v108
	ds_write_b32 v107, v197 offset:10864
	v_fma_f32 v12, -v180, v108, v12
	v_fma_f32 v226, v180, v110, v226
	v_fma_f32 v110, v179, v110, v12
	v_fma_f32 v108, v179, v108, v226
	v_cvt_pk_bf16_f32 v197, v110, v108
	ds_write_b32 v107, v197 offset:11136
	v_fma_f32 v13, -v180, v108, v13
	v_fma_f32 v227, v180, v110, v227
	v_fma_f32 v110, v179, v110, v13
	v_fma_f32 v108, v179, v108, v227
	v_cvt_pk_bf16_f32 v197, v110, v108
	ds_write_b32 v107, v197 offset:11408
	v_fma_f32 v14, -v180, v108, v14
	v_fma_f32 v228, v180, v110, v228
	v_fma_f32 v110, v179, v110, v14
	v_fma_f32 v108, v179, v108, v228
	v_cvt_pk_bf16_f32 v197, v110, v108
	ds_write_b32 v107, v197 offset:11680
	v_fma_f32 v15, -v180, v108, v15
	v_fma_f32 v229, v180, v110, v229
	v_fma_f32 v110, v179, v110, v15
	v_fma_f32 v108, v179, v108, v229
	v_cvt_pk_bf16_f32 v197, v110, v108
	ds_write_b32 v107, v197 offset:11952
	v_fma_f32 v246, -v180, v108, v246
	v_fma_f32 v210, v180, v110, v210
	v_fma_f32 v110, v179, v110, v246
	v_fma_f32 v108, v179, v108, v210
	v_cvt_pk_bf16_f32 v197, v110, v108
	ds_write_b32 v107, v197 offset:12224
	v_fma_f32 v247, -v180, v108, v247
	v_fma_f32 v211, v180, v110, v211
	v_fma_f32 v110, v179, v110, v247
	v_fma_f32 v108, v179, v108, v211
	v_cvt_pk_bf16_f32 v197, v110, v108
	ds_write_b32 v107, v197 offset:12496
	v_fma_f32 v248, -v180, v108, v248
	v_fma_f32 v212, v180, v110, v212
	v_fma_f32 v110, v179, v110, v248
	v_fma_f32 v108, v179, v108, v212
	v_cvt_pk_bf16_f32 v197, v110, v108
	ds_write_b32 v107, v197 offset:12768
	v_fma_f32 v249, -v180, v108, v249
	v_fma_f32 v213, v180, v110, v213
	v_fma_f32 v110, v179, v110, v249
	v_fma_f32 v108, v179, v108, v213
	v_cvt_pk_bf16_f32 v197, v110, v108
	ds_write_b32 v107, v197 offset:13040
	s_waitcnt lgkmcnt(0)
	ds_read_b128 v[214:217], v194 offset:4608
	ds_read_b128 v[218:221], v194 offset:4672
	ds_read_b128 v[222:225], v194 offset:4736
	ds_read_b128 v[226:229], v194 offset:4800
	ds_read_b128 v[234:237], v194 offset:8960
	ds_read_b128 v[238:241], v194 offset:9024
	ds_read_b128 v[242:245], v194 offset:9088
	ds_read_b128 v[246:249], v194 offset:9152
	ds_read_u16 v8, v195 offset:64
	ds_read_u16 v9, v195 offset:208
	ds_read_u16 v10, v195 offset:352
	ds_read_u16 v11, v195 offset:496
	ds_read_u16 v12, v195 offset:2368
	ds_read_u16 v13, v195 offset:2512
	ds_read_u16 v14, v195 offset:2656
	ds_read_u16 v15, v195 offset:2800
	s_waitcnt vmcnt(8) lgkmcnt(8)
	v_mfma_f32_16x16x32_bf16 v[0:3], v[214:217], v[44:47], 0
	v_mfma_f32_16x16x32_bf16 v[4:7], v[234:237], v[44:47], 0
	v_mfma_f32_16x16x32_bf16 v[0:3], v[218:221], v[40:43], v[0:3]
	v_mfma_f32_16x16x32_bf16 v[4:7], v[238:241], v[40:43], v[4:7]
	v_mfma_f32_16x16x32_bf16 v[0:3], v[222:225], v[32:35], v[0:3]
	v_mfma_f32_16x16x32_bf16 v[4:7], v[242:245], v[32:35], v[4:7]
	v_mfma_f32_16x16x32_bf16 v[0:3], v[226:229], v[36:39], v[0:3]
	v_mfma_f32_16x16x32_bf16 v[4:7], v[246:249], v[36:39], v[4:7]
	s_waitcnt lgkmcnt(0)
	v_lshlrev_b32_e32 v8, 16, v8
	v_lshlrev_b32_e32 v9, 16, v9
	v_lshlrev_b32_e32 v10, 16, v10
	v_lshlrev_b32_e32 v11, 16, v11
	v_lshlrev_b32_e32 v12, 16, v12
	v_lshlrev_b32_e32 v13, 16, v13
	v_lshlrev_b32_e32 v14, 16, v14
	v_lshlrev_b32_e32 v15, 16, v15
	v_mov_b32_e32 v206, 0x3d372713
	v_mov_b32_e32 v208, 0x3fcc422a
	v_mov_b32_e32 v210, 0xbfb8aa3b
	v_mov_b32_e32 v212, 1.0
	v_mov_b32_e32 v230, v181
	v_pk_fma_f32 v[0:1], v[230:231], v[8:9], v[0:1] op_sel_hi:[0,1,1]
	v_pk_fma_f32 v[2:3], v[230:231], v[10:11], v[2:3] op_sel_hi:[0,1,1]
	v_pk_fma_f32 v[4:5], v[230:231], v[12:13], v[4:5] op_sel_hi:[0,1,1]
	v_pk_fma_f32 v[6:7], v[230:231], v[14:15], v[6:7] op_sel_hi:[0,1,1]
	v_pk_mul_f32 v[198:199], v[0:1], v[206:207] op_sel_hi:[1,0]
	v_pk_mul_f32 v[200:201], v[2:3], v[206:207] op_sel_hi:[1,0]
	v_pk_mul_f32 v[202:203], v[4:5], v[206:207] op_sel_hi:[1,0]
	v_pk_mul_f32 v[204:205], v[6:7], v[206:207] op_sel_hi:[1,0]
	v_pk_mul_f32 v[198:199], v[0:1], v[198:199]
	v_pk_mul_f32 v[200:201], v[2:3], v[200:201]
	v_pk_mul_f32 v[202:203], v[4:5], v[202:203]
	v_pk_mul_f32 v[204:205], v[6:7], v[204:205]
	v_pk_fma_f32 v[198:199], v[0:1], v[198:199], v[0:1]
	v_pk_fma_f32 v[200:201], v[2:3], v[200:201], v[2:3]
	v_pk_fma_f32 v[202:203], v[4:5], v[202:203], v[4:5]
	v_pk_fma_f32 v[204:205], v[6:7], v[204:205], v[6:7]
	v_pk_mul_f32 v[198:199], v[198:199], v[208:209] op_sel_hi:[1,0]
	v_pk_mul_f32 v[200:201], v[200:201], v[208:209] op_sel_hi:[1,0]
	v_pk_mul_f32 v[202:203], v[202:203], v[208:209] op_sel_hi:[1,0]
	v_pk_mul_f32 v[204:205], v[204:205], v[208:209] op_sel_hi:[1,0]
	v_pk_mul_f32 v[198:199], v[198:199], v[210:211] op_sel_hi:[1,0]
	v_pk_mul_f32 v[200:201], v[200:201], v[210:211] op_sel_hi:[1,0]
	v_pk_mul_f32 v[202:203], v[202:203], v[210:211] op_sel_hi:[1,0]
	v_pk_mul_f32 v[204:205], v[204:205], v[210:211] op_sel_hi:[1,0]
	v_exp_f32_e32 v198, v198
	v_exp_f32_e32 v199, v199
	v_exp_f32_e32 v200, v200
	v_exp_f32_e32 v201, v201
	v_exp_f32_e32 v202, v202
	v_exp_f32_e32 v203, v203
	v_exp_f32_e32 v204, v204
	v_exp_f32_e32 v205, v205
	v_pk_add_f32 v[198:199], v[198:199], v[212:213] op_sel_hi:[1,0]
	v_pk_add_f32 v[200:201], v[200:201], v[212:213] op_sel_hi:[1,0]
	v_pk_add_f32 v[202:203], v[202:203], v[212:213] op_sel_hi:[1,0]
	v_pk_add_f32 v[204:205], v[204:205], v[212:213] op_sel_hi:[1,0]
	v_rcp_f32_e32 v198, v198
	v_rcp_f32_e32 v199, v199
	v_rcp_f32_e32 v200, v200
	v_rcp_f32_e32 v201, v201
	v_rcp_f32_e32 v202, v202
	v_rcp_f32_e32 v203, v203
	v_rcp_f32_e32 v204, v204
	v_rcp_f32_e32 v205, v205
	v_pk_mul_f32 v[0:1], v[0:1], v[198:199]
	v_pk_mul_f32 v[2:3], v[2:3], v[200:201]
	v_pk_mul_f32 v[4:5], v[4:5], v[202:203]
	v_pk_mul_f32 v[6:7], v[6:7], v[204:205]
	v_cvt_pk_bf16_f32 v0, v0, v101
	v_cvt_pk_bf16_f32 v1, v1, v101
	v_cvt_pk_bf16_f32 v2, v2, v101
	v_cvt_pk_bf16_f32 v3, v3, v101
	v_cvt_pk_bf16_f32 v4, v4, v101
	v_cvt_pk_bf16_f32 v5, v5, v101
	v_cvt_pk_bf16_f32 v6, v6, v101
	v_cvt_pk_bf16_f32 v7, v7, v101
	ds_write_b16 v195, v0 offset:64
	ds_write_b16 v195, v1 offset:208
	ds_write_b16 v195, v2 offset:352
	ds_write_b16 v195, v3 offset:496
	ds_write_b16 v195, v4 offset:2368
	ds_write_b16 v195, v5 offset:2512
	ds_write_b16 v195, v6 offset:2656
	ds_write_b16 v195, v7 offset:2800
	s_waitcnt lgkmcnt(0)
; #define LAS __attribute__((address_space(3)))
; template <bool PASS2>
; __device__ __forceinline__ void s5_tile(const Ctx& C, int T, int sb_lo, int sb_hi, LAS unsigned char* lds, int wave, int lane) {
;     ...
;         for (int gi = 0; gi < 4; ++gi) {
;             const int g = wave * 4 + gi, gnx = wave * 4 + ((gi + 1) & 3);
;             bfx8 bb[4], cm[4];
; #pragma unroll
;             for (int cb = 0; cb < 4; ++cb) { bb[cb] = bbn[cb]; bbn[cb] = *(const bfx8*)(BBt + ((size_t)(gnx * 128 + cb * 32 + tl)) * GN + 8 * hh); }
;             if (PASS2) {
; #pragma unroll
;                 for (int ks = 0; ks < 4; ++ks) { cm[ks] = cmn[ks]; cmn[ks] = *(const bfx8*)(CMt + ((size_t)(gnx * GN + fr)) * 128 + 32 * ks + 8 * kq); }
;             }
;             float s0ar = 0.f, s0ai = 0.f, s0br = 0.f, s0bi = 0.f;
;             if (sample) { const size_t o0 = ((size_t)(2 * sb) * NG + g) * NP + lane, o1 = o0 + (size_t)NG * NP;
;                 s0ar = C.in(2)[o0]; s0ai = C.in(3)[o0]; s0br = C.in(2)[o1]; s0bi = C.in(3)[o1]; }
;             const bfx8 a = *(const LAS bfx8*)(XU + tl * XU_STRIDE + 16 * gi + 8 * hh);
; #pragma unroll
;             for (int cb = 0; cb < 4; ++cb) {
;                 v16f acc;
; #pragma unroll
;                 for (int r = 0; r < 16; ++r) acc[r] = 0.f;
;                 acc = __builtin_amdgcn_mfma_f32_32x32x16_bf16(bb[cb], a, acc, 0, 0, 0);
; #pragma unroll
;                 for (int rg = 0; rg < 4; ++rg) { v2u w; w.x = cvt_pk_c(acc[4 * rg], acc[4 * rg + 1]); w.y = cvt_pk_c(acc[4 * rg + 2], acc[4 * rg + 3]);
;                     *(LAS v2u*)(BH + tl * BH_STRIDE + cb * 32 + 8 * rg + 4 * hh) = w; }
;             }
;             LDS_FENCE();
;             {
;                 unsigned bu[32];
; #pragma unroll
;                 for (int t = 0; t < 32; ++t) bu[t] = *(const LAS unsigned*)(BH + t * BH_STRIDE + 2 * lane);
;                 LDS_FENCE();
;                 float xr = sr[gi], xi = si[gi];
; #pragma unroll
;                 for (int t = 0; t < 32; ++t) {
;                     if (sample && t == 0) { xr = s0ar; xi = s0ai; }
;                     if (sample && t == 16) { xr = s0br; xi = s0bi; }
;                     const float nr = fmaf(lr[gi], xr, fmaf(-li[gi], xi, bf_lo(bu[t]))), ni = fmaf(lr[gi], xi, fmaf(li[gi], xr, bf_hi(bu[t])));
;                     xr = nr; xi = ni;
;                     if (PASS2) {
	global_load_dwordx4 v[76:79], v[124:125], off
	global_load_dwordx4 v[72:75], v[122:123], off
	global_load_dwordx4 v[68:71], v[120:121], off
	global_load_dwordx4 v[64:67], v[118:119], off
	ds_read_b128 v[250:253], v192 offset:96
	s_waitcnt vmcnt(11) lgkmcnt(0)
	v_mfma_f32_32x32x16_bf16 v[0:15], v[250:253], v[92:95], 0
	global_load_dwordx4 v[44:47], v[156:157], off
	global_load_dwordx4 v[40:43], v[156:157], off offset:1024
	global_load_dwordx4 v[36:39], v[156:157], off offset:2048
	global_load_dwordx4 v[32:35], v[156:157], off offset:3072
	s_waitcnt vmcnt(14)
	v_mfma_f32_32x32x16_bf16 v[214:229], v[250:253], v[88:91], 0
	s_waitcnt vmcnt(13)
	v_mfma_f32_32x32x16_bf16 v[234:249], v[250:253], v[84:87], 0
	s_waitcnt vmcnt(12)
	v_mfma_f32_32x32x16_bf16 v[198:213], v[250:253], v[80:83], 0
	s_nop 11
	v_permlane32_swap_b32_e32 v0, v234
	v_permlane32_swap_b32_e32 v1, v235
	v_permlane32_swap_b32_e32 v2, v236
	v_permlane32_swap_b32_e32 v3, v237
	v_permlane32_swap_b32_e32 v4, v238
	v_permlane32_swap_b32_e32 v5, v239
	v_permlane32_swap_b32_e32 v6, v240
	v_permlane32_swap_b32_e32 v7, v241
	v_permlane32_swap_b32_e32 v8, v242
	v_permlane32_swap_b32_e32 v9, v243
	v_permlane32_swap_b32_e32 v10, v244
	v_permlane32_swap_b32_e32 v11, v245
	v_permlane32_swap_b32_e32 v12, v246
	v_permlane32_swap_b32_e32 v13, v247
	v_permlane32_swap_b32_e32 v14, v248
	v_permlane32_swap_b32_e32 v15, v249
	v_permlane32_swap_b32_e32 v214, v198
	v_permlane32_swap_b32_e32 v215, v199
	v_permlane32_swap_b32_e32 v216, v200
	v_permlane32_swap_b32_e32 v217, v201
	v_permlane32_swap_b32_e32 v218, v202
	v_permlane32_swap_b32_e32 v219, v203
	v_permlane32_swap_b32_e32 v220, v204
	v_permlane32_swap_b32_e32 v221, v205
	v_permlane32_swap_b32_e32 v222, v206
	v_permlane32_swap_b32_e32 v223, v207
	v_permlane32_swap_b32_e32 v224, v208
	v_permlane32_swap_b32_e32 v225, v209
	v_permlane32_swap_b32_e32 v226, v210
	v_permlane32_swap_b32_e32 v227, v211
	v_permlane32_swap_b32_e32 v228, v212
	v_permlane32_swap_b32_e32 v229, v213
	v_fma_f32 v0, -v190, v109, v0
	v_fma_f32 v214, v190, v111, v214
	v_fma_f32 v111, v189, v111, v0
	v_fma_f32 v109, v189, v109, v214
	v_cvt_pk_bf16_f32 v197, v111, v109
	ds_write_b32 v107, v197 offset:4608
	v_fma_f32 v1, -v190, v109, v1
	v_fma_f32 v215, v190, v111, v215
	v_fma_f32 v111, v189, v111, v1
	v_fma_f32 v109, v189, v109, v215
	v_cvt_pk_bf16_f32 v197, v111, v109
	ds_write_b32 v107, v197 offset:4880
	v_fma_f32 v2, -v190, v109, v2
	v_fma_f32 v216, v190, v111, v216
	v_fma_f32 v111, v189, v111, v2
	v_fma_f32 v109, v189, v109, v216
	v_cvt_pk_bf16_f32 v197, v111, v109
	ds_write_b32 v107, v197 offset:5152
	v_fma_f32 v3, -v190, v109, v3
	v_fma_f32 v217, v190, v111, v217
	v_fma_f32 v111, v189, v111, v3
	v_fma_f32 v109, v189, v109, v217
	v_cvt_pk_bf16_f32 v197, v111, v109
	ds_write_b32 v107, v197 offset:5424
	v_fma_f32 v234, -v190, v109, v234
	v_fma_f32 v198, v190, v111, v198
	v_fma_f32 v111, v189, v111, v234
	v_fma_f32 v109, v189, v109, v198
	v_cvt_pk_bf16_f32 v197, v111, v109
	ds_write_b32 v107, v197 offset:5696
	v_fma_f32 v235, -v190, v109, v235
	v_fma_f32 v199, v190, v111, v199
	v_fma_f32 v111, v189, v111, v235
	v_fma_f32 v109, v189, v109, v199
	v_cvt_pk_bf16_f32 v197, v111, v109
	ds_write_b32 v107, v197 offset:5968
	v_fma_f32 v236, -v190, v109, v236
	v_fma_f32 v200, v190, v111, v200
	v_fma_f32 v111, v189, v111, v236
	v_fma_f32 v109, v189, v109, v200
	v_cvt_pk_bf16_f32 v197, v111, v109
	ds_write_b32 v107, v197 offset:6240
	v_fma_f32 v237, -v190, v109, v237
	v_fma_f32 v201, v190, v111, v201
	v_fma_f32 v111, v189, v111, v237
	v_fma_f32 v109, v189, v109, v201
	v_cvt_pk_bf16_f32 v197, v111, v109
	ds_write_b32 v107, v197 offset:6512
	v_fma_f32 v4, -v190, v109, v4
	v_fma_f32 v218, v190, v111, v218
	v_fma_f32 v111, v189, v111, v4
	v_fma_f32 v109, v189, v109, v218
	v_cvt_pk_bf16_f32 v197, v111, v109
	ds_write_b32 v107, v197 offset:6784
	v_fma_f32 v5, -v190, v109, v5
	v_fma_f32 v219, v190, v111, v219
	v_fma_f32 v111, v189, v111, v5
	v_fma_f32 v109, v189, v109, v219
	v_cvt_pk_bf16_f32 v197, v111, v109
	ds_write_b32 v107, v197 offset:7056
	v_fma_f32 v6, -v190, v109, v6
	v_fma_f32 v220, v190, v111, v220
	v_fma_f32 v111, v189, v111, v6
	v_fma_f32 v109, v189, v109, v220
	v_cvt_pk_bf16_f32 v197, v111, v109
	ds_write_b32 v107, v197 offset:7328
	v_fma_f32 v7, -v190, v109, v7
	v_fma_f32 v221, v190, v111, v221
	v_fma_f32 v111, v189, v111, v7
	v_fma_f32 v109, v189, v109, v221
	v_cvt_pk_bf16_f32 v197, v111, v109
	ds_write_b32 v107, v197 offset:7600
	v_fma_f32 v238, -v190, v109, v238
	v_fma_f32 v202, v190, v111, v202
	v_fma_f32 v111, v189, v111, v238
	v_fma_f32 v109, v189, v109, v202
	v_cvt_pk_bf16_f32 v197, v111, v109
	ds_write_b32 v107, v197 offset:7872
	v_fma_f32 v239, -v190, v109, v239
	v_fma_f32 v203, v190, v111, v203
	v_fma_f32 v111, v189, v111, v239
	v_fma_f32 v109, v189, v109, v203
	v_cvt_pk_bf16_f32 v197, v111, v109
	ds_write_b32 v107, v197 offset:8144
	v_fma_f32 v240, -v190, v109, v240
	v_fma_f32 v204, v190, v111, v204
	v_fma_f32 v111, v189, v111, v240
	v_fma_f32 v109, v189, v109, v204
	v_cvt_pk_bf16_f32 v197, v111, v109
	ds_write_b32 v107, v197 offset:8416
	v_fma_f32 v241, -v190, v109, v241
	v_fma_f32 v205, v190, v111, v205
	v_fma_f32 v111, v189, v111, v241
	v_fma_f32 v109, v189, v109, v205
	v_cvt_pk_bf16_f32 v197, v111, v109
	ds_write_b32 v107, v197 offset:8688
	v_fma_f32 v8, -v190, v109, v8
	v_fma_f32 v222, v190, v111, v222
	v_fma_f32 v111, v189, v111, v8
	v_fma_f32 v109, v189, v109, v222
	v_cvt_pk_bf16_f32 v197, v111, v109
	ds_write_b32 v107, v197 offset:8960
	v_fma_f32 v9, -v190, v109, v9
	v_fma_f32 v223, v190, v111, v223
	v_fma_f32 v111, v189, v111, v9
	v_fma_f32 v109, v189, v109, v223
; __device__ __forceinline__ float bf_lo(unsigned w) { return __uint_as_float(w << 16); }
; __device__ __forceinline__ float bf_hi(unsigned w) { return __uint_as_float(w & 0xffff0000u); }
; #define LAS __attribute__((address_space(3)))
; #define LDS_FENCE() asm volatile("s_waitcnt lgkmcnt(0)" ::: "memory")
; __device__ __forceinline__ unsigned cvt_pk_nv(float lo, float hi) { unsigned r; asm("v_cvt_pk_bf16_f32 %0, %1, %2" : "=v"(r) : "v"(lo), "v"(hi)); return r; }
;     __device__ __forceinline__ float* out() const { return (float*)karg_in(33); }
; template <bool PASS2>
; __device__ __forceinline__ void s5_tile(const Ctx& C, int T, int sb_lo, int sb_hi, LAS unsigned char* lds, int wave, int lane) {
;     ...
;                 for (int t = 0; t < 32; ++t) {
;                     if (sample && t == 0) { xr = s0ar; xi = s0ai; }
;                     if (sample && t == 16) { xr = s0br; xi = s0bi; }
;                     const float nr = fmaf(lr[gi], xr, fmaf(-li[gi], xi, bf_lo(bu[t]))), ni = fmaf(lr[gi], xi, fmaf(li[gi], xr, bf_hi(bu[t])));
;                     xr = nr; xi = ni;
;                     if (PASS2) {
;                         *(LAS unsigned*)(BH + t * BH_STRIDE + 2 * lane) = cvt_pk_nv(xr, xi);
;                         if (sample && (t & 15) == 15) { const int seq = 2 * sb + (t >> 4);
;                             C.out()[OFF_SRE_S + ((size_t)seq * NG + g) * NP + lane] = xr; C.out()[OFF_SIM_S + ((size_t)seq * NG + g) * NP + lane] = xi; }
;                     }
;                 }
;                 sr[gi] = xr; si[gi] = xi;
;             }
;             LDS_FENCE();
;             if (PASS2) {
; #pragma unroll
;                 for (int rb = 0; rb < 2; ++rb) {
;                     v4f acc = (v4f){0.f, 0.f, 0.f, 0.f};
; #pragma unroll
;                     for (int ks = 0; ks < 4; ++ks) {
;                         const bfx8 sa = *(const LAS bfx8*)(BH + (16 * rb + fr) * BH_STRIDE + 32 * ks + 8 * kq);
;                         acc = __builtin_amdgcn_mfma_f32_16x16x32_bf16(sa, cm[ks], acc, 0, 0, 0);
;                     }
; #pragma unroll
;                     for (int r = 0; r < 4; ++r) {
;                         LAS bf16* up = XU + (16 * rb + 4 * kq + r) * XU_STRIDE + 16 * gi + fr;
	v_cvt_pk_bf16_f32 v197, v111, v109
	ds_write_b32 v107, v197 offset:9232
	v_fma_f32 v10, -v190, v109, v10
	v_fma_f32 v224, v190, v111, v224
	v_fma_f32 v111, v189, v111, v10
	v_fma_f32 v109, v189, v109, v224
	v_cvt_pk_bf16_f32 v197, v111, v109
	ds_write_b32 v107, v197 offset:9504
	v_fma_f32 v11, -v190, v109, v11
	v_fma_f32 v225, v190, v111, v225
	v_fma_f32 v111, v189, v111, v11
	v_fma_f32 v109, v189, v109, v225
	v_cvt_pk_bf16_f32 v197, v111, v109
	ds_write_b32 v107, v197 offset:9776
	v_fma_f32 v242, -v190, v109, v242
	v_fma_f32 v206, v190, v111, v206
	v_fma_f32 v111, v189, v111, v242
	v_fma_f32 v109, v189, v109, v206
	v_cvt_pk_bf16_f32 v197, v111, v109
	ds_write_b32 v107, v197 offset:10048
	v_fma_f32 v243, -v190, v109, v243
	v_fma_f32 v207, v190, v111, v207
	v_fma_f32 v111, v189, v111, v243
	v_fma_f32 v109, v189, v109, v207
	v_cvt_pk_bf16_f32 v197, v111, v109
	ds_write_b32 v107, v197 offset:10320
	v_fma_f32 v244, -v190, v109, v244
	v_fma_f32 v208, v190, v111, v208
	v_fma_f32 v111, v189, v111, v244
	v_fma_f32 v109, v189, v109, v208
	v_cvt_pk_bf16_f32 v197, v111, v109
	ds_write_b32 v107, v197 offset:10592
	v_fma_f32 v245, -v190, v109, v245
	v_fma_f32 v209, v190, v111, v209
	v_fma_f32 v111, v189, v111, v245
	v_fma_f32 v109, v189, v109, v209
	v_cvt_pk_bf16_f32 v197, v111, v109
	ds_write_b32 v107, v197 offset:10864
	v_fma_f32 v12, -v190, v109, v12
	v_fma_f32 v226, v190, v111, v226
	v_fma_f32 v111, v189, v111, v12
	v_fma_f32 v109, v189, v109, v226
	v_cvt_pk_bf16_f32 v197, v111, v109
	ds_write_b32 v107, v197 offset:11136
	v_fma_f32 v13, -v190, v109, v13
	v_fma_f32 v227, v190, v111, v227
	v_fma_f32 v111, v189, v111, v13
	v_fma_f32 v109, v189, v109, v227
	v_cvt_pk_bf16_f32 v197, v111, v109
	ds_write_b32 v107, v197 offset:11408
	v_fma_f32 v14, -v190, v109, v14
	v_fma_f32 v228, v190, v111, v228
	v_fma_f32 v111, v189, v111, v14
	v_fma_f32 v109, v189, v109, v228
	v_cvt_pk_bf16_f32 v197, v111, v109
	ds_write_b32 v107, v197 offset:11680
	v_fma_f32 v15, -v190, v109, v15
	v_fma_f32 v229, v190, v111, v229
	v_fma_f32 v111, v189, v111, v15
	v_fma_f32 v109, v189, v109, v229
	v_cvt_pk_bf16_f32 v197, v111, v109
	ds_write_b32 v107, v197 offset:11952
	v_fma_f32 v246, -v190, v109, v246
	v_fma_f32 v210, v190, v111, v210
	v_fma_f32 v111, v189, v111, v246
	v_fma_f32 v109, v189, v109, v210
	v_cvt_pk_bf16_f32 v197, v111, v109
	ds_write_b32 v107, v197 offset:12224
	v_fma_f32 v247, -v190, v109, v247
	v_fma_f32 v211, v190, v111, v211
	v_fma_f32 v111, v189, v111, v247
	v_fma_f32 v109, v189, v109, v211
	v_cvt_pk_bf16_f32 v197, v111, v109
	ds_write_b32 v107, v197 offset:12496
	v_fma_f32 v248, -v190, v109, v248
	v_fma_f32 v212, v190, v111, v212
	v_fma_f32 v111, v189, v111, v248
	v_fma_f32 v109, v189, v109, v212
	v_cvt_pk_bf16_f32 v197, v111, v109
	ds_write_b32 v107, v197 offset:12768
	v_fma_f32 v249, -v190, v109, v249
	v_fma_f32 v213, v190, v111, v213
	v_fma_f32 v111, v189, v111, v249
	v_fma_f32 v109, v189, v109, v213
	v_cvt_pk_bf16_f32 v197, v111, v109
	ds_write_b32 v107, v197 offset:13040
	s_waitcnt lgkmcnt(0)
	ds_read_b128 v[214:217], v194 offset:4608
	ds_read_b128 v[218:221], v194 offset:4672
	ds_read_b128 v[222:225], v194 offset:4736
	ds_read_b128 v[226:229], v194 offset:4800
	ds_read_b128 v[234:237], v194 offset:8960
	ds_read_b128 v[238:241], v194 offset:9024
	ds_read_b128 v[242:245], v194 offset:9088
	ds_read_b128 v[246:249], v194 offset:9152
	ds_read_u16 v8, v195 offset:96
	ds_read_u16 v9, v195 offset:240
	ds_read_u16 v10, v195 offset:384
	ds_read_u16 v11, v195 offset:528
	ds_read_u16 v12, v195 offset:2400
	ds_read_u16 v13, v195 offset:2544
	ds_read_u16 v14, v195 offset:2688
	ds_read_u16 v15, v195 offset:2832
	s_waitcnt vmcnt(8) lgkmcnt(8)
	v_mfma_f32_16x16x32_bf16 v[0:3], v[214:217], v[60:63], 0
	v_mfma_f32_16x16x32_bf16 v[4:7], v[234:237], v[60:63], 0
	v_mfma_f32_16x16x32_bf16 v[0:3], v[218:221], v[56:59], v[0:3]
	v_mfma_f32_16x16x32_bf16 v[4:7], v[238:241], v[56:59], v[4:7]
	v_mfma_f32_16x16x32_bf16 v[0:3], v[222:225], v[48:51], v[0:3]
	v_mfma_f32_16x16x32_bf16 v[4:7], v[242:245], v[48:51], v[4:7]
	v_mfma_f32_16x16x32_bf16 v[0:3], v[226:229], v[52:55], v[0:3]
	v_mfma_f32_16x16x32_bf16 v[4:7], v[246:249], v[52:55], v[4:7]
	s_waitcnt lgkmcnt(0)
; __device__ __forceinline__ float gelu_t(float x) { const float u = 1.5957691216057308f * (x + 0.044715f * x * x * x); return x * sigmoid_f(u); }
; #define LAS __attribute__((address_space(3)))
; #define LDS_FENCE() asm volatile("s_waitcnt lgkmcnt(0)" ::: "memory")
; __device__ __forceinline__ bf16 f2bf(float f) { return (bf16)(cvt_pk_nv(f, 0.f) & 0xffffu); }
; __device__ __forceinline__ float sigmoid_f(float x) { return __builtin_amdgcn_rcpf(1.0f + __expf(-x)); }
; __device__ __forceinline__ float silu_f(float x) { return x * sigmoid_f(x); }
; template <bool PASS2>
; __device__ __forceinline__ void s5_tile(const Ctx& C, int T, int sb_lo, int sb_hi, LAS unsigned char* lds, int wave, int lane) {
;     ...
;                         const float u = __uint_as_float((unsigned)(*up) << 16);
;                         *up = f2bf(gelu_t(acc[r] + dsk[gi] * u));
;                     }
;                 }
;                 LDS_FENCE();
;             }
;         }
;         if (PASS2) {
; #pragma unroll
;             for (int i = 0; i < 4; ++i) *(v4u*)(C.YB() + (size_t)(rb0 + xrow + 8 * i) * BWD + 64 * wave + 8 * xpart) = *(const LAS v4u*)(XU + (xrow + 8 * i) * XU_STRIDE + 8 * xpart);
	v_lshlrev_b32_e32 v8, 16, v8
	v_lshlrev_b32_e32 v9, 16, v9
	v_lshlrev_b32_e32 v10, 16, v10
	v_lshlrev_b32_e32 v11, 16, v11
	v_lshlrev_b32_e32 v12, 16, v12
	v_lshlrev_b32_e32 v13, 16, v13
	v_lshlrev_b32_e32 v14, 16, v14
	v_lshlrev_b32_e32 v15, 16, v15
	v_mov_b32_e32 v206, 0x3d372713
	v_mov_b32_e32 v208, 0x3fcc422a
	v_mov_b32_e32 v210, 0xbfb8aa3b
	v_mov_b32_e32 v212, 1.0
	v_mov_b32_e32 v230, v191
	v_pk_fma_f32 v[0:1], v[230:231], v[8:9], v[0:1] op_sel_hi:[0,1,1]
	v_pk_fma_f32 v[2:3], v[230:231], v[10:11], v[2:3] op_sel_hi:[0,1,1]
	v_pk_fma_f32 v[4:5], v[230:231], v[12:13], v[4:5] op_sel_hi:[0,1,1]
	v_pk_fma_f32 v[6:7], v[230:231], v[14:15], v[6:7] op_sel_hi:[0,1,1]
	v_pk_mul_f32 v[198:199], v[0:1], v[206:207] op_sel_hi:[1,0]
	v_pk_mul_f32 v[200:201], v[2:3], v[206:207] op_sel_hi:[1,0]
	v_pk_mul_f32 v[202:203], v[4:5], v[206:207] op_sel_hi:[1,0]
	v_pk_mul_f32 v[204:205], v[6:7], v[206:207] op_sel_hi:[1,0]
	v_pk_mul_f32 v[198:199], v[0:1], v[198:199]
	v_pk_mul_f32 v[200:201], v[2:3], v[200:201]
	v_pk_mul_f32 v[202:203], v[4:5], v[202:203]
	v_pk_mul_f32 v[204:205], v[6:7], v[204:205]
	v_pk_fma_f32 v[198:199], v[0:1], v[198:199], v[0:1]
	v_pk_fma_f32 v[200:201], v[2:3], v[200:201], v[2:3]
	v_pk_fma_f32 v[202:203], v[4:5], v[202:203], v[4:5]
	v_pk_fma_f32 v[204:205], v[6:7], v[204:205], v[6:7]
	v_pk_mul_f32 v[198:199], v[198:199], v[208:209] op_sel_hi:[1,0]
	v_pk_mul_f32 v[200:201], v[200:201], v[208:209] op_sel_hi:[1,0]
	v_pk_mul_f32 v[202:203], v[202:203], v[208:209] op_sel_hi:[1,0]
	v_pk_mul_f32 v[204:205], v[204:205], v[208:209] op_sel_hi:[1,0]
	v_pk_mul_f32 v[198:199], v[198:199], v[210:211] op_sel_hi:[1,0]
	v_pk_mul_f32 v[200:201], v[200:201], v[210:211] op_sel_hi:[1,0]
	v_pk_mul_f32 v[202:203], v[202:203], v[210:211] op_sel_hi:[1,0]
	v_pk_mul_f32 v[204:205], v[204:205], v[210:211] op_sel_hi:[1,0]
	v_exp_f32_e32 v198, v198
	v_exp_f32_e32 v199, v199
	v_exp_f32_e32 v200, v200
	v_exp_f32_e32 v201, v201
	v_exp_f32_e32 v202, v202
	v_exp_f32_e32 v203, v203
	v_exp_f32_e32 v204, v204
	v_exp_f32_e32 v205, v205
	v_pk_add_f32 v[198:199], v[198:199], v[212:213] op_sel_hi:[1,0]
	v_pk_add_f32 v[200:201], v[200:201], v[212:213] op_sel_hi:[1,0]
	v_pk_add_f32 v[202:203], v[202:203], v[212:213] op_sel_hi:[1,0]
	v_pk_add_f32 v[204:205], v[204:205], v[212:213] op_sel_hi:[1,0]
	v_rcp_f32_e32 v198, v198
	v_rcp_f32_e32 v199, v199
	v_rcp_f32_e32 v200, v200
	v_rcp_f32_e32 v201, v201
	v_rcp_f32_e32 v202, v202
	v_rcp_f32_e32 v203, v203
	v_rcp_f32_e32 v204, v204
	v_rcp_f32_e32 v205, v205
	v_pk_mul_f32 v[0:1], v[0:1], v[198:199]
	v_pk_mul_f32 v[2:3], v[2:3], v[200:201]
	v_pk_mul_f32 v[4:5], v[4:5], v[202:203]
	v_pk_mul_f32 v[6:7], v[6:7], v[204:205]
	v_cvt_pk_bf16_f32 v0, v0, v101
	v_cvt_pk_bf16_f32 v1, v1, v101
	v_cvt_pk_bf16_f32 v2, v2, v101
	v_cvt_pk_bf16_f32 v3, v3, v101
	v_cvt_pk_bf16_f32 v4, v4, v101
	v_cvt_pk_bf16_f32 v5, v5, v101
	v_cvt_pk_bf16_f32 v6, v6, v101
	v_cvt_pk_bf16_f32 v7, v7, v101
	ds_write_b16 v195, v0 offset:96
	ds_write_b16 v195, v1 offset:240
	ds_write_b16 v195, v2 offset:384
	ds_write_b16 v195, v3 offset:528
	ds_write_b16 v195, v4 offset:2400
	ds_write_b16 v195, v5 offset:2544
	ds_write_b16 v195, v6 offset:2688
	ds_write_b16 v195, v7 offset:2832
	v_ashrrev_i32_e32 v159, 31, v158
	v_lshlrev_b64 v[4:5], 10, v[158:159]
	s_waitcnt lgkmcnt(0)
	ds_read_b128 v[0:3], v196
	s_load_dwordx2 s[0:1], s[0:1], 0x110
	s_waitcnt lgkmcnt(0)
	v_lshl_add_u64 v[4:5], s[0:1], 0, v[4:5]
	v_lshl_add_u64 v[4:5], v[4:5], 0, s[10:11]
	v_lshl_add_u64 v[4:5], v[4:5], 0, v[100:101]
	v_add_co_u32_e32 v4, vcc, s47, v4
	s_mov_b64 s[0:1], s[80:81]
	s_nop 0
	v_addc_co_u32_e32 v5, vcc, 0, v5, vcc
	global_store_dwordx4 v[4:5], v[0:3], off
	ds_read_b128 v[0:3], v196 offset:1152
	s_load_dwordx2 s[0:1], s[0:1], 0x110
	v_add_u32_e32 v4, 8, v158
	v_ashrrev_i32_e32 v5, 31, v4
	v_lshlrev_b64 v[4:5], 10, v[4:5]
	s_waitcnt lgkmcnt(0)
	v_lshl_add_u64 v[4:5], s[0:1], 0, v[4:5]
	v_lshl_add_u64 v[4:5], v[4:5], 0, s[10:11]
	v_lshl_add_u64 v[4:5], v[4:5], 0, v[100:101]
	v_add_co_u32_e32 v4, vcc, s47, v4
	s_mov_b64 s[0:1], s[80:81]
	s_nop 0
	v_addc_co_u32_e32 v5, vcc, 0, v5, vcc
	global_store_dwordx4 v[4:5], v[0:3], off
	ds_read_b128 v[0:3], v196 offset:2304
	s_load_dwordx2 s[0:1], s[0:1], 0x110
	v_add_u32_e32 v4, 16, v158
	v_ashrrev_i32_e32 v5, 31, v4
	v_lshlrev_b64 v[4:5], 10, v[4:5]
	s_waitcnt lgkmcnt(0)
	v_lshl_add_u64 v[4:5], s[0:1], 0, v[4:5]
	v_lshl_add_u64 v[4:5], v[4:5], 0, s[10:11]
	v_lshl_add_u64 v[4:5], v[4:5], 0, v[100:101]
	v_add_co_u32_e32 v4, vcc, s47, v4
	s_mov_b64 s[0:1], s[80:81]
	s_nop 0
	v_addc_co_u32_e32 v5, vcc, 0, v5, vcc
	global_store_dwordx4 v[4:5], v[0:3], off
	ds_read_b128 v[0:3], v196 offset:3456
	s_load_dwordx2 s[0:1], s[0:1], 0x110
	v_add_u32_e32 v4, 24, v158
	v_ashrrev_i32_e32 v5, 31, v4
	v_lshlrev_b64 v[4:5], 10, v[4:5]
	s_waitcnt lgkmcnt(0)
	v_lshl_add_u64 v[4:5], s[0:1], 0, v[4:5]
	v_lshl_add_u64 v[4:5], v[4:5], 0, s[10:11]
	v_lshl_add_u64 v[4:5], v[4:5], 0, v[100:101]
	v_add_co_u32_e32 v4, vcc, 0x11300000, v4
	s_nop 1
	v_addc_co_u32_e32 v5, vcc, 0, v5, vcc
	global_store_dwordx4 v[4:5], v[0:3], off
	s_waitcnt lgkmcnt(0)
	s_cbranch_scc1 .LBB0_671
